# MLA attention: wave halves skewed by one barrier segment + setprio + 5-deep K-fragment prefetch; in_cd epilogue table loads hoisted ahead of stores
# speedup vs baseline: 1.0084x; 1.0045x over previous
; __device__ __forceinline__ int v_st(int k, int c) { const int kk = (k & ~0xC) | ((k & 4) << 1) | ((k & 8) >> 1); return ((kk >> 3) * 4 + (c >> 5)) * 512 + ((kk & 7) * 32 + (c & 31)) * 2; }
; __device__ __forceinline__ int v_rd_base(int lane) { return ((lane & 3) << 3) | (((lane >> 2) & 3) << 6) | (((lane >> 4) & 1) << 5) | (((lane >> 5) & 1) << 8); }
; template <int DQK, int MODE, int SDEPTH, int ldq, int ldk, int ldv, int ldo, int ldg> ...
;     ...
;   int tid_ = threadIdx.x; asm volatile("" : "+v"(tid_));
;   const int tid = tid_, wid = tid >> 6, lane = tid & 63, r32 = lane & 31, hi = lane >> 5;
;   char* V_lds = lds; char* K_lds = lds + 2 * SH::V;
;   float* ws = (float*)(lds + SH::WSO) + wid * 64; float* li_l = ws; float* al_l = ws + 32;
;   float m_reg = -1e30f, l_reg = 0; f32x16 o[4] = {}; bf16x8 qr[ND];
;   const bf16_t* Qw = Qb + (long)(wid * QBLK + r32) * ldq + hi * 8;
; #pragma unroll
;   for (int d0 = 0; d0 < ND; ++d0) qr[d0] = *reinterpret_cast<const bf16x8*>(Qw + d0 * 16);
;   const int sr = tid >> 4, sc = (tid & 15) * 8, vst0 = v_st(sr, sc), vst1 = v_st(32 + sr, sc);
;   int krow[KPT], kcol[KPT];
; #pragma unroll
;   for (int i = 0; i < KPT; ++i) { const int id = tid + 512 * i; krow[i] = id / NKC; kcol[i] = (id % NKC) * 8; }
;   const int vb0 = (int)(uintptr_t)V_lds + v_rd_base(lane);
;   struct { bf16x8 vs0, vs1, ks[KPT]; } sr_[SDEPTH == 0 ? 1 : SDEPTH];
;   constexpr int SE = 0, SO = SDEPTH == 2 ? 1 : 0;
.LBB0_827:
	s_or_b64 exec, exec, s[4:5]
	s_add_u32 s35, s26, 0x15400000
	s_addc_u32 s36, s27, 0
	s_add_u32 s30, s26, 0x18a00000
	s_addc_u32 s34, s27, 0
	s_add_u32 s28, s26, 0x1c000000
	s_addc_u32 s29, s27, 0
	s_lshl_b32 s5, s92, 8
	s_ashr_i32 s8, s92, 5
	s_and_b32 s5, s5, 0x700
	s_bfe_u32 s9, s92, 0x20003
	s_mul_i32 s4, s8, 0x900
	s_add_i32 s38, s5, 0x100
	s_mul_hi_i32 s3, s8, 0x900
	s_add_u32 s14, s4, s38
	s_addc_u32 s15, s3, 0
	s_mul_i32 s3, s15, 0x600
	s_mul_hi_u32 s4, s14, 0x600
	s_add_i32 s4, s4, s3
	s_mul_i32 s3, s14, 0x600
	s_add_u32 s3, s35, s3
	s_mul_i32 s39, s9, 0xc0
	s_addc_u32 s5, s36, s4
	s_lshl_b32 s6, s39, 1
	s_add_u32 s4, s3, s6
	s_addc_u32 s5, s5, 0
	s_mul_i32 s7, s8, 0x360000
	s_mul_hi_i32 s3, s8, 0x360000
	s_add_u32 s7, s30, s7
	s_addc_u32 s3, s34, s3
	s_add_u32 s6, s7, s6
	s_addc_u32 s7, s3, 0
	s_mul_i32 s13, s8, 0x240000
	s_mul_hi_i32 s3, s8, 0x240000
	s_add_u32 s13, s28, s13
	s_addc_u32 s17, s29, s3
	s_lshl_b32 s3, s9, 7
	s_lshl_b32 s37, s9, 8
	s_add_u32 s16, s13, s37
	v_mov_b32_e32 v20, v0
	s_mov_b32 s13, 0x2aaaaaab
	s_addc_u32 s17, s17, 0
	s_waitcnt lgkmcnt(1)
	v_mul_hi_i32 v1, v20, s13
	v_lshrrev_b32_e32 v3, 31, v1
	v_ashrrev_i32_e32 v1, 2, v1
	v_add_u32_e32 v22, v1, v3
	v_mul_lo_u32 v1, v22, 24
	v_sub_u32_e32 v23, v20, v1
	v_add_u32_e32 v1, 0x200, v20
	v_mul_hi_i32 v3, v1, s13
	v_lshrrev_b32_e32 v5, 31, v3
	v_ashrrev_i32_e32 v3, 2, v3
	v_add_u32_e32 v24, v3, v5
	v_mul_lo_u32 v3, v24, 24
	v_sub_u32_e32 v25, v1, v3
	v_add_u32_e32 v1, 0x400, v20
	v_mul_hi_i32 v3, v1, s13
	v_lshrrev_b32_e32 v5, 31, v3
	v_ashrrev_i32_e32 v3, 2, v3
	v_add_u32_e32 v26, v3, v5
	v_ashrrev_i32_e32 v2, 4, v20
	v_mul_lo_u32 v3, v26, 24
	v_lshlrev_b32_e32 v21, 3, v20
	v_add_u32_e32 v4, 32, v2
	v_sub_u32_e32 v27, v1, v3
	v_ashrrev_i32_e32 v3, 31, v2
	v_mov_b32_e32 v169, 0
	v_and_b32_e32 v166, 0x78, v21
	v_lshlrev_b64 v[12:13], 10, v[2:3]
	v_ashrrev_i32_e32 v5, 31, v4
	v_lshl_add_u64 v[14:15], s[16:17], 0, v[12:13]
	v_lshlrev_b32_e32 v16, 1, v166
	v_mov_b32_e32 v17, v169
	v_lshlrev_b64 v[18:19], 10, v[4:5]
	v_lshlrev_b32_e32 v6, 3, v23
	v_lshl_add_u64 v[14:15], v[14:15], 0, v[16:17]
	v_lshl_add_u64 v[18:19], s[16:17], 0, v[18:19]
	s_movk_i32 s12, 0x600
	v_lshl_add_u64 v[16:17], v[18:19], 0, v[16:17]
	global_load_dwordx4 v[98:101], v[14:15], off
	global_load_dwordx4 v[102:105], v[16:17], off
	v_ashrrev_i32_e32 v7, 31, v6
	v_mov_b64_e32 v[14:15], s[6:7]
	v_mad_i64_i32 v[16:17], s[6:7], v22, s12, v[14:15]
	v_lshlrev_b64 v[6:7], 1, v[6:7]
	v_lshlrev_b32_e32 v8, 3, v25
	v_lshlrev_b32_e32 v10, 3, v27
	v_lshl_add_u64 v[16:17], v[16:17], 0, v[6:7]
	global_load_dwordx4 v[106:109], v[16:17], off
	v_ashrrev_i32_e32 v9, 31, v8
	v_ashrrev_i32_e32 v11, 31, v10
	v_mad_i64_i32 v[16:17], s[6:7], v24, s12, v[14:15]
	v_lshlrev_b64 v[8:9], 1, v[8:9]
	v_mad_i64_i32 v[14:15], s[6:7], v26, s12, v[14:15]
	v_lshlrev_b64 v[10:11], 1, v[10:11]
	v_ashrrev_i32_e32 v167, 6, v20
	v_lshl_add_u64 v[16:17], v[16:17], 0, v[8:9]
	v_lshl_add_u64 v[14:15], v[14:15], 0, v[10:11]
	v_and_b32_e32 v180, 31, v20
	v_and_b32_e32 v3, 0x3fffffc0, v20
	s_add_i32 s31, 0, 0x14000
	v_lshlrev_b32_e32 v170, 5, v167
	global_load_dwordx4 v[110:113], v[16:17], off
	global_load_dwordx4 v[134:137], v[14:15], off
	v_bfe_u32 v181, v20, 5, 1
	v_lshl_add_u32 v171, v3, 2, s31
	v_or_b32_e32 v3, v170, v180
	v_mov_b64_e32 v[14:15], s[4:5]
	v_mad_i64_i32 v[14:15], s[4:5], v3, s12, v[14:15]
	v_lshlrev_b32_e32 v168, 4, v181
	v_lshl_add_u64 v[14:15], v[14:15], 0, v[168:169]
	global_load_dwordx4 v[114:117], v[14:15], off
	global_load_dwordx4 v[118:121], v[14:15], off offset:32
	global_load_dwordx4 v[122:125], v[14:15], off offset:64
	global_load_dwordx4 v[126:129], v[14:15], off offset:96
	global_load_dwordx4 v[130:133], v[14:15], off offset:128
	global_load_dwordx4 v[138:141], v[14:15], off offset:160
	global_load_dwordx4 v[142:145], v[14:15], off offset:192
	global_load_dwordx4 v[146:149], v[14:15], off offset:224
	global_load_dwordx4 v[150:153], v[14:15], off offset:256
	global_load_dwordx4 v[154:157], v[14:15], off offset:288
	global_load_dwordx4 v[158:161], v[14:15], off offset:320
	global_load_dwordx4 v[162:165], v[14:15], off offset:352
	v_and_b32_e32 v3, 0xfffff0, v2
	v_lshlrev_b32_e32 v5, 1, v2
	v_and_or_b32 v3, v5, 8, v3
	v_lshrrev_b32_e32 v5, 1, v2
	v_lshrrev_b32_e32 v3, 1, v3
	v_bfe_u32 v14, v21, 5, 2
	v_and_b32_e32 v2, 3, v2
	v_or_b32_e32 v3, v3, v14
	v_and_or_b32 v2, v5, 4, v2
	v_lshlrev_b32_e32 v16, 9, v3
	v_lshlrev_b32_e32 v17, 6, v2
	v_and_b32_e32 v2, 0xfffff0, v4
	v_lshlrev_b32_e32 v3, 1, v4
	v_and_or_b32 v2, v3, 8, v2
	v_lshrrev_b32_e32 v2, 1, v2
	v_lshlrev_b32_e32 v18, 4, v20
	v_or_b32_e32 v2, v2, v14
	v_and_b32_e32 v19, 48, v18
	v_lshlrev_b32_e32 v2, 9, v2
	v_or3_b32 v183, v16, v17, v19
	v_or3_b32 v182, v2, v17, v19
	v_add_u32_e32 v16, 0, v183
	s_waitcnt vmcnt(0)
; __device__ __forceinline__ int v_st(int k, int c) { const int kk = (k & ~0xC) | ((k & 4) << 1) | ((k & 8) >> 1); return ((kk >> 3) * 4 + (c >> 5)) * 512 + ((kk & 7) * 32 + (c & 31)) * 2; }
; __device__ __forceinline__ int v_rd_base(int lane) { return ((lane & 3) << 3) | (((lane >> 2) & 3) << 6) | (((lane >> 4) & 1) << 5) | (((lane >> 5) & 1) << 8); }
; #define SLOAD(i, k0) do { sr_[i].vs0 = *reinterpret_cast<const bf16x8*>(&Vh[(long)((k0) + sr) * ldv + sc]); sr_[i].vs1 = *reinterpret_cast<const bf16x8*>(&Vh[(long)((k0) + 32 + sr) * ldv + sc]); \
;     _Pragma("unroll") for (int q_ = 0; q_ < KPT; ++q_) sr_[i].ks[q_] = *reinterpret_cast<const bf16x8*>(&Kh[(long)((k0) + krow[q_]) * ldk + kcol[q_]]); } while (0)
; #define SWRITE(b, i) do { *(bf16x8*)(V_lds + (b) * SH::V + vst0) = sr_[i].vs0; *(bf16x8*)(V_lds + (b) * SH::V + vst1) = sr_[i].vs1; \
;     _Pragma("unroll") for (int q_ = 0; q_ < KPT; ++q_) *(bf16x8*)(K_lds + (b) * SH::K + KSWZ(krow[q_], kcol[q_] * 2)) = sr_[i].ks[q_]; } while (0)
; template <int DQK, int MODE, int SDEPTH, int ldq, int ldk, int ldv, int ldo, int ldg> ...
;     ...
;   float m_reg = -1e30f, l_reg = 0; f32x16 o[4] = {}; bf16x8 qr[ND];
;   const bf16_t* Qw = Qb + (long)(wid * QBLK + r32) * ldq + hi * 8;
; #pragma unroll
;   for (int d0 = 0; d0 < ND; ++d0) qr[d0] = *reinterpret_cast<const bf16x8*>(Qw + d0 * 16);
;   const int sr = tid >> 4, sc = (tid & 15) * 8, vst0 = v_st(sr, sc), vst1 = v_st(32 + sr, sc);
;   int krow[KPT], kcol[KPT];
; #pragma unroll
;   for (int i = 0; i < KPT; ++i) { const int id = tid + 512 * i; krow[i] = id / NKC; kcol[i] = (id % NKC) * 8; }
;   const int vb0 = (int)(uintptr_t)V_lds + v_rd_base(lane);
;   struct { bf16x8 vs0, vs1, ks[KPT]; } sr_[SDEPTH == 0 ? 1 : SDEPTH];
;   constexpr int SE = 0, SO = SDEPTH == 2 ? 1 : 0;
;     ...
;   const int qb4 = n0 >> 6;
;   const float nlane = (float)(n0 + wid * QBLK + r32 - 4 * hi);
;     ...
;   f32x16 pA0, pA1, pB0, pB1; float mnA = 0.f, mnB = 0.f, alA = 1.f, alB = 1.f; bf16x8 pa0, pa1, pa2, pa3; const int NT = seq / KVBLK;
;   if constexpr (SDEPTH == 0) {
;     SLOAD(0, 0); asm volatile("s_waitcnt vmcnt(0)" ::: "memory"); SWRITE(0, 0); __syncthreads();
	v_mad_i64_i32 v[2:3], s[4:5], v22, s12, 0
	v_mad_i64_i32 v[4:5], s[4:5], v24, s12, 0
	v_mad_i64_i32 v[14:15], s[4:5], v26, s12, 0
	s_movk_i32 s12, 0x180
	v_mul_lo_u32 v184, v22, s12
	s_movk_i32 s6, 0x100
	v_mul_lo_u32 v186, v24, s12
	v_and_b32_e32 v19, 0x70, v18
	v_bitop3_b32 v200, v168, v19, s6 bitop3:0x36
	s_movk_i32 s6, 0x120
	v_bitop3_b32 v201, v168, v19, s6 bitop3:0x36
	s_movk_i32 s6, 0x140
	v_mul_lo_u32 v188, v26, s12
	v_lshlrev_b32_e32 v17, 1, v20
	v_bitop3_b32 v202, v168, v19, s6 bitop3:0x36
	s_movk_i32 s6, 0x160
	v_and_b32_e32 v17, 32, v17
	s_waitcnt vmcnt(16)
	ds_write_b128 v16, v[98:101]
	v_add_u32_e32 v16, 0, v182
	s_waitcnt vmcnt(15)
	ds_write_b128 v16, v[102:105]
	v_bitop3_b32 v16, v22, v23, 7 bitop3:0x6c
	v_lshlrev_b32_e32 v185, 4, v16
	v_add3_u32 v16, 0, v184, v185
	v_bitop3_b32 v203, v168, v19, s6 bitop3:0x36
	s_movk_i32 s6, 0x118
	s_cmp_lg_u32 0, -1
	s_movk_i32 s7, 0xc0
	s_waitcnt vmcnt(14)
	ds_write_b128 v16, v[106:109] offset:32768
	v_bitop3_b32 v16, v24, v25, 7 bitop3:0x6c
	v_lshlrev_b32_e32 v187, 4, v16
	v_add3_u32 v16, 0, v186, v187
	v_and_or_b32 v17, v21, s6, v17
	s_cselect_b32 s6, 0, 0
	s_movk_i32 s16, 0x70
	v_bitop3_b32 v198, v168, v19, s7 bitop3:0x36
	s_movk_i32 s7, 0xe0
	v_bitop3_b32 v192, v168, v18, s16 bitop3:0x78
	v_bitop3_b32 v199, v168, v19, s7 bitop3:0x36
	v_mad_u32_u24 v191, v180, s12, 0
	s_movk_i32 s12, 0x60
	v_bitop3_b32 v195, v168, v19, s12 bitop3:0x36
	s_movk_i32 s12, 0x80
	v_bitop3_b32 v196, v168, v19, s12 bitop3:0x36
	s_waitcnt vmcnt(13)
	ds_write_b128 v16, v[110:113] offset:32768
	v_bitop3_b32 v16, v26, v27, 7 bitop3:0x6c
	v_lshlrev_b32_e32 v189, 4, v16
	v_add3_u32 v16, 0, v188, v189
	s_waitcnt vmcnt(12)
	ds_write_b128 v16, v[134:137] offset:32768
	v_and_b32_e32 v16, 0xc0, v18
	v_add3_u32 v204, v16, s6, v17
	v_mov_b32_e32 v16, 0x360000
	v_mad_i64_i32 v[14:15], s[6:7], s8, v16, v[14:15]
	v_mov_b32_e32 v17, 0x180
	v_mad_i64_i32 v[2:3], s[16:17], s8, v16, v[2:3]
	v_mad_u64_u32 v[14:15], s[6:7], s9, v17, v[14:15]
	v_mad_i64_i32 v[4:5], s[16:17], s8, v16, v[4:5]
	v_mad_u64_u32 v[2:3], s[16:17], s9, v17, v[2:3]
	s_mov_b64 s[6:7], 0x18a18000
	v_mad_u64_u32 v[4:5], s[16:17], s9, v17, v[4:5]
	v_lshl_add_u64 v[2:3], v[2:3], 0, v[6:7]
	v_lshl_add_u64 v[10:11], v[14:15], 0, v[10:11]
	v_lshl_add_u64 v[4:5], v[4:5], 0, v[8:9]
	v_lshl_add_u64 v[176:177], v[2:3], 0, s[6:7]
	v_mov_b32_e32 v2, 0x240000
	v_lshl_add_u64 v[172:173], v[10:11], 0, s[6:7]
	v_lshl_add_u64 v[174:175], v[4:5], 0, s[6:7]
	v_mad_i64_i32 v[178:179], s[6:7], s8, v2, v[12:13]
	v_and_b32_e32 v2, 15, v20
	s_movk_i32 s12, 0xa0
	v_lshlrev_b32_e32 v2, 4, v2
	v_mov_b32_e32 v16, v169
	v_mov_b32_e32 v17, v169
	s_mov_b32 s13, 0
	v_and_b32_e32 v1, 63, v20
	v_bitop3_b32 v193, v168, v19, 32 bitop3:0x36
	v_bitop3_b32 v194, v168, v19, 64 bitop3:0x36
	v_bitop3_b32 v197, v168, v19, s12 bitop3:0x36
	v_or3_b32 v178, v178, s37, v2
	v_mov_b32_e32 v2, v169
	v_mov_b32_e32 v3, v169
	v_mov_b32_e32 v4, v169
	v_mov_b32_e32 v5, v169
	v_mov_b32_e32 v6, v169
	v_mov_b32_e32 v7, v169
	v_mov_b32_e32 v8, v169
	v_mov_b32_e32 v9, v169
	v_mov_b32_e32 v10, v169
	v_mov_b32_e32 v11, v169
	v_mov_b32_e32 v12, v169
	v_mov_b32_e32 v13, v169
	v_mov_b32_e32 v14, v169
	v_mov_b32_e32 v15, v169
	v_mov_b64_e32 v[64:65], v[16:17]
	v_mov_b64_e32 v[48:49], v[16:17]
	v_mov_b64_e32 v[32:33], v[16:17]
	v_cmp_gt_u32_e64 s[4:5], 32, v1
	v_lshl_add_u32 v190, v180, 2, v171
	s_mul_i32 s12, s9, 0x180
	v_mov_b32_e32 v205, 0xf149f2ca
	s_mov_b32 s40, 0x42ddb3d8
	s_mov_b64 s[8:9], 0x18000
	s_mov_b64 s[16:17], 0x10000
	v_mov_b64_e32 v[62:63], v[14:15]
	v_mov_b64_e32 v[60:61], v[12:13]
	v_mov_b64_e32 v[58:59], v[10:11]
	v_mov_b64_e32 v[56:57], v[8:9]
	v_mov_b64_e32 v[54:55], v[6:7]
	v_mov_b64_e32 v[52:53], v[4:5]
	v_mov_b64_e32 v[50:51], v[2:3]
	v_mov_b64_e32 v[46:47], v[14:15]
	v_mov_b64_e32 v[44:45], v[12:13]
	v_mov_b64_e32 v[42:43], v[10:11]
	v_mov_b64_e32 v[40:41], v[8:9]
	v_mov_b64_e32 v[38:39], v[6:7]
	v_mov_b64_e32 v[36:37], v[4:5]
	v_mov_b64_e32 v[34:35], v[2:3]
	v_mov_b64_e32 v[30:31], v[14:15]
	v_mov_b64_e32 v[28:29], v[12:13]
	v_mov_b64_e32 v[26:27], v[10:11]
	v_mov_b64_e32 v[24:25], v[8:9]
	v_mov_b64_e32 v[22:23], v[6:7]
	v_mov_b64_e32 v[20:21], v[4:5]
	v_mov_b64_e32 v[18:19], v[2:3]
	s_mov_b32 s41, s13
	s_waitcnt lgkmcnt(0)
	s_barrier
	s_cmp_ge_u32 s93, 4
	s_cbranch_scc1 .Lm1_B_entry
	s_cmp_lt_u32 s41, 35
	s_cselect_b64 s[18:19], -1, 0
	s_cmp_gt_u32 s41, 34
	s_cbranch_scc1 .LBB0_829

; template <int DQK>
; __device__ __forceinline__ void partialSM(f32x16& p0, f32x16& p1, float& m_reg, float& mn, float& alpha) {
;     ...
;   float pmax = p0[0];
; #pragma unroll
;   for (int r = 1; r < 16; ++r) pmax = fmaxf(pmax, p0[r]);
; #pragma unroll
;   for (int r = 0; r < 16; ++r) pmax = fmaxf(pmax, p1[r]);
;   { auto rr = __builtin_amdgcn_permlane32_swap(__float_as_uint(pmax), __float_as_uint(pmax), false, false);
;     pmax = fmaxf(__uint_as_float(rr[0]), __uint_as_float(rr[1])); }
;   if (__builtin_expect(__all(pmax - m_reg <= THR / SCALE), 1)) { mn = m_reg; alpha = 1.f; }
;   else { mn = fmaxf(m_reg, pmax); alpha = __builtin_amdgcn_exp2f((m_reg - mn) * C); m_reg = mn; }
.LBB0_829:
	s_setprio 1
	s_and_b32 s42, s41, 1
	s_mul_i32 s6, s42, 0x6000
	v_add_u32_e32 v222, s6, v191
	v_add_u32_e32 v223, v222, v192
	ds_read_b128 v[206:209], v223 offset:32768
	ds_read_b128 v[210:213], v223 offset:45056
	v_add_u32_e32 v223, v222, v193
	ds_read_b128 v[214:217], v223 offset:32768
	ds_read_b128 v[218:221], v223 offset:45056
	v_add_u32_e32 v223, v222, v194
	ds_read_b128 v[228:231], v223 offset:32768
	ds_read_b128 v[232:235], v223 offset:45056
	v_add_u32_e32 v223, v222, v195
	ds_read_b128 v[236:239], v223 offset:32768
	ds_read_b128 v[240:243], v223 offset:45056
	v_add_u32_e32 v223, v222, v196
	ds_read_b128 v[244:247], v223 offset:32768
	ds_read_b128 v[248:251], v223 offset:45056
	s_waitcnt lgkmcnt(9)
	v_mfma_f32_32x32x16_bf16 v[82:97], v[206:209], v[114:117], 0
	s_waitcnt lgkmcnt(8)
	v_mfma_f32_32x32x16_bf16 v[66:81], v[210:213], v[114:117], 0
	v_add_u32_e32 v223, v222, v197
	ds_read_b128 v[206:209], v223 offset:32768
	ds_read_b128 v[210:213], v223 offset:45056
	s_waitcnt lgkmcnt(9)
	v_mfma_f32_32x32x16_bf16 v[82:97], v[214:217], v[118:121], v[82:97]
	s_waitcnt lgkmcnt(8)
	v_mfma_f32_32x32x16_bf16 v[66:81], v[218:221], v[118:121], v[66:81]
	v_add_u32_e32 v223, v222, v198
	ds_read_b128 v[214:217], v223 offset:32768
	ds_read_b128 v[218:221], v223 offset:45056
	s_waitcnt lgkmcnt(9)
	v_mfma_f32_32x32x16_bf16 v[82:97], v[228:231], v[122:125], v[82:97]
	s_waitcnt lgkmcnt(8)
	v_mfma_f32_32x32x16_bf16 v[66:81], v[232:235], v[122:125], v[66:81]
	v_add_u32_e32 v223, v222, v199
	ds_read_b128 v[228:231], v223 offset:32768
	ds_read_b128 v[232:235], v223 offset:45056
	s_waitcnt lgkmcnt(9)
	v_mfma_f32_32x32x16_bf16 v[82:97], v[236:239], v[126:129], v[82:97]
	s_waitcnt lgkmcnt(8)
	v_mfma_f32_32x32x16_bf16 v[66:81], v[240:243], v[126:129], v[66:81]
	v_add_u32_e32 v223, v222, v200
	ds_read_b128 v[236:239], v223 offset:32768
	ds_read_b128 v[240:243], v223 offset:45056
	s_waitcnt lgkmcnt(9)
	v_mfma_f32_32x32x16_bf16 v[82:97], v[244:247], v[130:133], v[82:97]
	s_waitcnt lgkmcnt(8)
	v_mfma_f32_32x32x16_bf16 v[66:81], v[248:251], v[130:133], v[66:81]
	v_add_u32_e32 v223, v222, v201
	ds_read_b128 v[244:247], v223 offset:32768
	ds_read_b128 v[248:251], v223 offset:45056
	s_waitcnt lgkmcnt(9)
	v_mfma_f32_32x32x16_bf16 v[82:97], v[206:209], v[138:141], v[82:97]
	s_waitcnt lgkmcnt(8)
	v_mfma_f32_32x32x16_bf16 v[66:81], v[210:213], v[138:141], v[66:81]
	v_add_u32_e32 v223, v222, v202
	ds_read_b128 v[206:209], v223 offset:32768
	ds_read_b128 v[210:213], v223 offset:45056
	s_waitcnt lgkmcnt(9)
	v_mfma_f32_32x32x16_bf16 v[82:97], v[214:217], v[142:145], v[82:97]
	s_waitcnt lgkmcnt(8)
	v_mfma_f32_32x32x16_bf16 v[66:81], v[218:221], v[142:145], v[66:81]
	v_add_u32_e32 v223, v222, v203
	ds_read_b128 v[214:217], v223 offset:32768
	ds_read_b128 v[218:221], v223 offset:45056
	s_waitcnt lgkmcnt(9)
	v_mfma_f32_32x32x16_bf16 v[82:97], v[228:231], v[146:149], v[82:97]
	s_waitcnt lgkmcnt(8)
	v_mfma_f32_32x32x16_bf16 v[66:81], v[232:235], v[146:149], v[66:81]
	s_waitcnt lgkmcnt(7)
	v_mfma_f32_32x32x16_bf16 v[82:97], v[236:239], v[150:153], v[82:97]
	s_waitcnt lgkmcnt(6)
	v_mfma_f32_32x32x16_bf16 v[66:81], v[240:243], v[150:153], v[66:81]
	s_waitcnt lgkmcnt(5)
	v_mfma_f32_32x32x16_bf16 v[82:97], v[244:247], v[154:157], v[82:97]
	s_waitcnt lgkmcnt(4)
	v_mfma_f32_32x32x16_bf16 v[66:81], v[248:251], v[154:157], v[66:81]
	s_waitcnt lgkmcnt(3)
	v_mfma_f32_32x32x16_bf16 v[82:97], v[206:209], v[158:161], v[82:97]
	s_waitcnt lgkmcnt(2)
	v_mfma_f32_32x32x16_bf16 v[66:81], v[210:213], v[158:161], v[66:81]
	s_waitcnt lgkmcnt(1)
	v_mfma_f32_32x32x16_bf16 v[82:97], v[214:217], v[162:165], v[82:97]
	s_waitcnt lgkmcnt(0)
	v_mfma_f32_32x32x16_bf16 v[66:81], v[218:221], v[162:165], v[66:81]
	s_setprio 0
	s_nop 10
	v_max_f32_e32 v206, v83, v83
	v_max_f32_e32 v207, v82, v82
	v_max_f32_e32 v206, v207, v206
	v_max3_f32 v206, v206, v84, v85
	v_max3_f32 v206, v206, v86, v87
	v_max3_f32 v206, v206, v88, v89
	v_max3_f32 v206, v206, v90, v91
	v_max3_f32 v206, v206, v92, v93
	v_max3_f32 v206, v206, v94, v95
	v_max3_f32 v206, v206, v96, v97
	v_max3_f32 v206, v206, v66, v67
	v_max3_f32 v206, v206, v68, v69
	v_max3_f32 v206, v206, v70, v71
	v_max3_f32 v206, v206, v72, v73
	v_max3_f32 v206, v206, v74, v75
	v_max3_f32 v206, v206, v76, v77
	v_max3_f32 v206, v206, v78, v79
	v_max3_f32 v206, v206, v80, v81
	v_mov_b32_e32 v207, v206
	s_nop 1
	v_permlane32_swap_b32_e32 v206, v207
	v_max_f32_e32 v207, v207, v207
	v_max_f32_e32 v206, v206, v206
	v_max_f32_e32 v206, v206, v207
	v_max_f32_e32 v207, v205, v205
	v_max_f32_e32 v207, v207, v206
	v_sub_f32_e32 v208, v206, v205
	v_sub_f32_e32 v206, v205, v207
	v_mul_f32_e32 v206, 0x3dd53b94, v206
	v_exp_f32_e32 v206, v206
	v_cmp_ge_f32_e32 vcc, s40, v208
	s_cmp_eq_u64 vcc, exec
	s_cselect_b64 s[6:7], -1, 0
	v_cndmask_b32_e64 v206, v206, 1.0, s[6:7]
	v_cmp_gt_f32_e32 vcc, 1.0, v206
	s_cbranch_vccz .LBB0_833
	s_and_saveexec_b64 s[54:55], s[4:5]
	ds_write_b32 v190, v206 offset:128
	s_or_b64 exec, exec, s[54:55]
	s_waitcnt lgkmcnt(0)
	v_add_u32_e32 v220, v171, v168
	ds_read_b128 v[208:211], v220 offset:224
	ds_read_b128 v[212:215], v220 offset:192
	ds_read_b128 v[216:219], v220 offset:160
	ds_read_b128 v[220:223], v220 offset:128
	s_waitcnt lgkmcnt(3)
	v_pk_mul_f32 v[14:15], v[14:15], v[208:209]
	s_waitcnt lgkmcnt(2)
	v_pk_mul_f32 v[10:11], v[10:11], v[212:213]
	s_waitcnt lgkmcnt(1)
	v_pk_mul_f32 v[6:7], v[6:7], v[216:217]
	v_pk_mul_f32 v[16:17], v[16:17], v[210:211]
	v_pk_mul_f32 v[12:13], v[12:13], v[214:215]
	v_pk_mul_f32 v[8:9], v[8:9], v[218:219]
	s_waitcnt lgkmcnt(0)
	v_pk_mul_f32 v[4:5], v[4:5], v[222:223]
	v_pk_mul_f32 v[2:3], v[2:3], v[220:221]
	v_pk_mul_f32 v[62:63], v[62:63], v[208:209]
	v_pk_mul_f32 v[58:59], v[58:59], v[212:213]
	v_pk_mul_f32 v[54:55], v[54:55], v[216:217]
	v_pk_mul_f32 v[64:65], v[64:65], v[210:211]
	v_pk_mul_f32 v[60:61], v[60:61], v[214:215]
	v_pk_mul_f32 v[56:57], v[56:57], v[218:219]
	v_pk_mul_f32 v[52:53], v[52:53], v[222:223]
	v_pk_mul_f32 v[50:51], v[50:51], v[220:221]
	v_pk_mul_f32 v[46:47], v[46:47], v[208:209]
	v_pk_mul_f32 v[42:43], v[42:43], v[212:213]
	v_pk_mul_f32 v[38:39], v[38:39], v[216:217]
	v_pk_mul_f32 v[48:49], v[48:49], v[210:211]
	v_pk_mul_f32 v[44:45], v[44:45], v[214:215]
	v_pk_mul_f32 v[40:41], v[40:41], v[218:219]
	v_pk_mul_f32 v[36:37], v[36:37], v[222:223]
	v_pk_mul_f32 v[34:35], v[34:35], v[220:221]
	v_pk_mul_f32 v[30:31], v[30:31], v[208:209]
	v_pk_mul_f32 v[26:27], v[26:27], v[212:213]
	v_pk_mul_f32 v[22:23], v[22:23], v[216:217]
	v_pk_mul_f32 v[32:33], v[32:33], v[210:211]
	v_pk_mul_f32 v[28:29], v[28:29], v[214:215]
	v_pk_mul_f32 v[24:25], v[24:25], v[218:219]
	v_pk_mul_f32 v[20:21], v[20:21], v[222:223]
	v_pk_mul_f32 v[18:19], v[18:19], v[220:221]
; template <int D0> __device__ __forceinline__ void pv_one(f32x16& od, int vb, bf16x8 pa0, bf16x8 pa1, bf16x8 pa2, bf16x8 pa3) {
;   const s16x4 l0 = tr_read<v_rd_off(D0, 0, 0)>(vb), h0 = tr_read<v_rd_off(D0, 0, 1)>(vb), l1 = tr_read<v_rd_off(D0, 1, 0)>(vb), h1 = tr_read<v_rd_off(D0, 1, 1)>(vb);
;   const s16x4 l2 = tr_read<v_rd_off(D0, 2, 0)>(vb), h2 = tr_read<v_rd_off(D0, 2, 1)>(vb), l3 = tr_read<v_rd_off(D0, 3, 0)>(vb), h3 = tr_read<v_rd_off(D0, 3, 1)>(vb);
;   asm volatile("s_waitcnt lgkmcnt(0)" ::: "memory"); SBAR();
;     ...
;   od = __builtin_amdgcn_mfma_f32_32x32x16_bf16(pa0, PK(l0, h0), od, 0, 0, 0);
;   od = __builtin_amdgcn_mfma_f32_32x32x16_bf16(pa1, PK(l1, h1), od, 0, 0, 0);
;   od = __builtin_amdgcn_mfma_f32_32x32x16_bf16(pa2, PK(l2, h2), od, 0, 0, 0);
;   od = __builtin_amdgcn_mfma_f32_32x32x16_bf16(pa3, PK(l3, h3), od, 0, 0, 0);
;     ...
; }
; __device__ __forceinline__ void pv_d0(f32x16* o, int vb, bf16x8 pa0, bf16x8 pa1, bf16x8 pa2, bf16x8 pa3) {
;   pv_one<0>(o[0], vb, pa0, pa1, pa2, pa3); pv_one<1>(o[1], vb, pa0, pa1, pa2, pa3); pv_one<2>(o[2], vb, pa0, pa1, pa2, pa3); pv_one<3>(o[3], vb, pa0, pa1, pa2, pa3);
; }
; __device__ __forceinline__ void pack_p(const f32x16& p0, const f32x16& p1, bf16x8& pa0, bf16x8& pa1, bf16x8& pa2, bf16x8& pa3) {
;     ...
;   PK4(p0, 0, pa0); PK4(p0, 8, pa1); PK4(p1, 0, pa2); PK4(p1, 8, pa3);
;     ...
; }
; template <int DQK>
; __device__ __forceinline__ void partialSM(f32x16& p0, f32x16& p1, float& m_reg, float& mn, float& alpha) {
;   constexpr float SCALE = DQK == 128 ? 0.088388347648318440f : 0.072168783648703220f;
;   constexpr float C = SCALE * LOG2E;
;   float pmax = p0[0];
; #pragma unroll
;   for (int r = 1; r < 16; ++r) pmax = fmaxf(pmax, p0[r]);
; #pragma unroll
;   for (int r = 0; r < 16; ++r) pmax = fmaxf(pmax, p1[r]);
;   { auto rr = __builtin_amdgcn_permlane32_swap(__float_as_uint(pmax), __float_as_uint(pmax), false, false);
;     pmax = fmaxf(__uint_as_float(rr[0]), __uint_as_float(rr[1])); }
;   if (__builtin_expect(__all(pmax - m_reg <= THR / SCALE), 1)) { mn = m_reg; alpha = 1.f; }
;   else { mn = fmaxf(m_reg, pmax); alpha = __builtin_amdgcn_exp2f((m_reg - mn) * C); m_reg = mn; }
;   const float mnC = -mn * C;
; #pragma unroll
;   for (int r = 0; r < 16; ++r) p0[r] = fmaf(p0[r], C, mnC);
; #pragma unroll
;   for (int r = 0; r < 16; ++r) p1[r] = fmaf(p1[r], C, mnC);
; #pragma unroll
.LBB0_833:
	v_cndmask_b32_e64 v205, v207, v205, s[6:7]
	s_barrier
	v_mul_f32_e32 v207, 0xbdd53b94, v205
	v_fmamk_f32 v82, v82, 0x3dd53b94, v207
	v_fmamk_f32 v83, v83, 0x3dd53b94, v207
	v_fmamk_f32 v84, v84, 0x3dd53b94, v207
	v_fmamk_f32 v85, v85, 0x3dd53b94, v207
	v_fmamk_f32 v86, v86, 0x3dd53b94, v207
	v_fmamk_f32 v87, v87, 0x3dd53b94, v207
	v_fmamk_f32 v88, v88, 0x3dd53b94, v207
	v_fmamk_f32 v89, v89, 0x3dd53b94, v207
	v_fmamk_f32 v90, v90, 0x3dd53b94, v207
	v_fmamk_f32 v91, v91, 0x3dd53b94, v207
	v_fmamk_f32 v92, v92, 0x3dd53b94, v207
	v_fmamk_f32 v93, v93, 0x3dd53b94, v207
	v_fmamk_f32 v94, v94, 0x3dd53b94, v207
	v_fmamk_f32 v95, v95, 0x3dd53b94, v207
	v_fmamk_f32 v96, v96, 0x3dd53b94, v207
	v_fmamk_f32 v97, v97, 0x3dd53b94, v207
	v_fmamk_f32 v66, v66, 0x3dd53b94, v207
	v_fmamk_f32 v67, v67, 0x3dd53b94, v207
	v_fmamk_f32 v68, v68, 0x3dd53b94, v207
	v_fmamk_f32 v69, v69, 0x3dd53b94, v207
	v_fmamk_f32 v70, v70, 0x3dd53b94, v207
	v_fmamk_f32 v71, v71, 0x3dd53b94, v207
	v_fmamk_f32 v72, v72, 0x3dd53b94, v207
	v_fmamk_f32 v73, v73, 0x3dd53b94, v207
	v_fmamk_f32 v74, v74, 0x3dd53b94, v207
	v_fmamk_f32 v75, v75, 0x3dd53b94, v207
	v_fmamk_f32 v76, v76, 0x3dd53b94, v207
	v_fmamk_f32 v77, v77, 0x3dd53b94, v207
	v_fmamk_f32 v78, v78, 0x3dd53b94, v207
	v_fmamk_f32 v79, v79, 0x3dd53b94, v207
	v_fmamk_f32 v80, v80, 0x3dd53b94, v207
	v_fmac_f32_e32 v207, 0x3dd53b94, v81
	v_exp_f32_e32 v81, v82
	v_exp_f32_e32 v82, v83
	v_exp_f32_e32 v83, v84
	v_exp_f32_e32 v84, v85
	v_exp_f32_e32 v85, v86
	v_exp_f32_e32 v86, v87
	v_exp_f32_e32 v87, v88
	v_exp_f32_e32 v88, v89
	v_exp_f32_e32 v89, v90
	v_exp_f32_e32 v90, v91
	v_exp_f32_e32 v91, v92
	v_exp_f32_e32 v92, v93
	v_exp_f32_e32 v93, v94
	v_exp_f32_e32 v94, v95
	v_exp_f32_e32 v95, v96
	v_exp_f32_e32 v96, v97
	v_exp_f32_e32 v97, v66
	v_add_f32_e32 v66, 0, v81
	v_add_f32_e32 v66, v82, v66
	v_add_f32_e32 v66, v83, v66
	v_add_f32_e32 v66, v84, v66
	v_add_f32_e32 v66, v85, v66
	v_add_f32_e32 v66, v86, v66
	v_add_f32_e32 v66, v87, v66
	v_add_f32_e32 v66, v88, v66
	v_add_f32_e32 v66, v89, v66
	v_add_f32_e32 v66, v90, v66
	v_add_f32_e32 v66, v91, v66
	v_add_f32_e32 v66, v92, v66
	v_add_f32_e32 v66, v93, v66
	v_exp_f32_e32 v208, v67
	v_add_f32_e32 v66, v94, v66
	v_exp_f32_e32 v209, v68
	v_add_f32_e32 v66, v95, v66
	v_exp_f32_e32 v210, v69
	v_add_f32_e32 v66, v96, v66
	v_exp_f32_e32 v211, v70
	v_add_f32_e32 v66, v97, v66
	v_exp_f32_e32 v212, v71
	v_add_f32_e32 v66, v208, v66
	v_exp_f32_e32 v213, v72
	v_add_f32_e32 v66, v209, v66
	v_exp_f32_e32 v214, v73
	v_add_f32_e32 v66, v210, v66
	v_exp_f32_e32 v215, v74
	v_add_f32_e32 v66, v211, v66
	v_exp_f32_e32 v216, v75
	v_add_f32_e32 v66, v212, v66
	v_exp_f32_e32 v217, v76
	v_add_f32_e32 v66, v213, v66
	v_exp_f32_e32 v218, v77
	v_add_f32_e32 v66, v214, v66
	v_exp_f32_e32 v219, v78
	v_add_f32_e32 v66, v215, v66
	v_exp_f32_e32 v220, v79
	v_add_f32_e32 v66, v216, v66
	v_exp_f32_e32 v221, v80
	v_add_f32_e32 v66, v217, v66
	v_exp_f32_e32 v207, v207
	v_add_f32_e32 v66, v218, v66
	v_add_f32_e32 v66, v219, v66
	v_add_f32_e32 v66, v220, v66
	v_add_f32_e32 v66, v221, v66
	v_add_f32_e32 v66, v207, v66
	v_mov_b32_e32 v67, v66
	s_nop 1
	v_permlane32_swap_b32_e32 v66, v67
	v_cvt_pk_bf16_f32 v68, v81, v82
	v_cvt_pk_bf16_f32 v69, v83, v84
	v_cvt_pk_bf16_f32 v70, v85, v86
	v_cvt_pk_bf16_f32 v71, v87, v88
	v_cvt_pk_bf16_f32 v72, v89, v90
	v_cvt_pk_bf16_f32 v73, v91, v92
	v_cvt_pk_bf16_f32 v74, v93, v94
	v_cvt_pk_bf16_f32 v75, v95, v96
	v_cvt_pk_bf16_f32 v76, v97, v208
	v_cvt_pk_bf16_f32 v77, v209, v210
	v_cvt_pk_bf16_f32 v78, v211, v212
	v_cvt_pk_bf16_f32 v79, v213, v214
	v_cvt_pk_bf16_f32 v80, v215, v216
	v_cvt_pk_bf16_f32 v81, v217, v218
	v_cvt_pk_bf16_f32 v82, v219, v220
	v_cvt_pk_bf16_f32 v83, v221, v207
	v_permlane32_swap_b32_e32 v68, v70
	v_permlane32_swap_b32_e32 v69, v71
	v_permlane32_swap_b32_e32 v72, v74
	v_permlane32_swap_b32_e32 v73, v75
	v_permlane32_swap_b32_e32 v76, v78
	v_permlane32_swap_b32_e32 v77, v79
	v_permlane32_swap_b32_e32 v80, v82
	v_permlane32_swap_b32_e32 v81, v83
	v_lshl_add_u32 v96, s42, 14, v204
	s_setprio 1
	ds_read_b64_tr_b16 v[84:85], v96 offset:0
	ds_read_b64_tr_b16 v[86:87], v96 offset:0x800
	ds_read_b64_tr_b16 v[88:89], v96 offset:0x1000
	ds_read_b64_tr_b16 v[90:91], v96 offset:0x1800
	ds_read_b64_tr_b16 v[92:93], v96 offset:0x2000
	ds_read_b64_tr_b16 v[94:95], v96 offset:0x2800
	ds_read_b64_tr_b16 v[208:209], v96 offset:0x3000
	ds_read_b64_tr_b16 v[210:211], v96 offset:0x3800
	s_waitcnt lgkmcnt(0)
	s_nop 0
	v_mfma_f32_32x32x16_bf16 v[2:17], v[68:71], v[84:87], v[2:17]
	ds_read_b64_tr_b16 v[84:85], v96 offset:0x200
	ds_read_b64_tr_b16 v[86:87], v96 offset:0xa00
	v_mfma_f32_32x32x16_bf16 v[2:17], v[72:75], v[88:91], v[2:17]
	ds_read_b64_tr_b16 v[88:89], v96 offset:0x1200
	ds_read_b64_tr_b16 v[90:91], v96 offset:0x1a00
	v_mfma_f32_32x32x16_bf16 v[2:17], v[76:79], v[92:95], v[2:17]
	ds_read_b64_tr_b16 v[92:93], v96 offset:0x2200
	ds_read_b64_tr_b16 v[94:95], v96 offset:0x2a00
	ds_read_b64_tr_b16 v[212:213], v96 offset:0x3200
	ds_read_b64_tr_b16 v[214:215], v96 offset:0x3a00
	s_waitcnt lgkmcnt(0)
	v_mfma_f32_32x32x16_bf16 v[2:17], v[80:83], v[208:211], v[2:17]
	v_mfma_f32_32x32x16_bf16 v[50:65], v[68:71], v[84:87], v[50:65]
	ds_read_b64_tr_b16 v[84:85], v96 offset:0x400
	ds_read_b64_tr_b16 v[86:87], v96 offset:0xc00
	v_mfma_f32_32x32x16_bf16 v[50:65], v[72:75], v[88:91], v[50:65]
	ds_read_b64_tr_b16 v[88:89], v96 offset:0x1400
	ds_read_b64_tr_b16 v[90:91], v96 offset:0x1c00
	v_mfma_f32_32x32x16_bf16 v[50:65], v[76:79], v[92:95], v[50:65]
	ds_read_b64_tr_b16 v[92:93], v96 offset:0x2400
	ds_read_b64_tr_b16 v[94:95], v96 offset:0x2c00
	ds_read_b64_tr_b16 v[208:209], v96 offset:0x3400
	ds_read_b64_tr_b16 v[210:211], v96 offset:0x3c00
	s_waitcnt lgkmcnt(0)
	v_mfma_f32_32x32x16_bf16 v[50:65], v[80:83], v[212:215], v[50:65]
	v_mfma_f32_32x32x16_bf16 v[34:49], v[68:71], v[84:87], v[34:49]
	ds_read_b64_tr_b16 v[84:85], v96 offset:0x600
	ds_read_b64_tr_b16 v[86:87], v96 offset:0xe00
	v_mfma_f32_32x32x16_bf16 v[34:49], v[72:75], v[88:91], v[34:49]
	ds_read_b64_tr_b16 v[88:89], v96 offset:0x1600
	ds_read_b64_tr_b16 v[90:91], v96 offset:0x1e00
	v_mfma_f32_32x32x16_bf16 v[34:49], v[76:79], v[92:95], v[34:49]
	ds_read_b64_tr_b16 v[92:93], v96 offset:0x2600
	ds_read_b64_tr_b16 v[94:95], v96 offset:0x2e00
	ds_read_b64_tr_b16 v[212:213], v96 offset:0x3600
	ds_read_b64_tr_b16 v[214:215], v96 offset:0x3e00
	s_waitcnt lgkmcnt(0)
	v_mfma_f32_32x32x16_bf16 v[34:49], v[80:83], v[208:211], v[34:49]
	v_mfma_f32_32x32x16_bf16 v[18:33], v[68:71], v[84:87], v[18:33]
	s_andn2_b64 vcc, exec, s[18:19]
	v_mfma_f32_32x32x16_bf16 v[18:33], v[72:75], v[88:91], v[18:33]
	v_mfma_f32_32x32x16_bf16 v[18:33], v[76:79], v[92:95], v[18:33]
	v_mfma_f32_32x32x16_bf16 v[18:33], v[80:83], v[212:215], v[18:33]
	s_setprio 0
	s_cbranch_vccnz .LBB0_835
; #define SWRITE(b, i) do { *(bf16x8*)(V_lds + (b) * SH::V + vst0) = sr_[i].vs0; *(bf16x8*)(V_lds + (b) * SH::V + vst1) = sr_[i].vs1; \
;     _Pragma("unroll") for (int q_ = 0; q_ < KPT; ++q_) *(bf16x8*)(K_lds + (b) * SH::K + KSWZ(krow[q_], kcol[q_] * 2)) = sr_[i].ks[q_]; } while (0)
; template <int DQK, int MODE, int SDEPTH, int ldq, int ldk, int ldv, int ldo, int ldg> ...
;     ...
;       if (j + 1 < NT) { asm volatile("s_waitcnt vmcnt(0)" ::: "memory"); SWRITE(bsel ^ 1, 0); }
	s_xor_b32 s6, s42, 1
	s_lshl_b32 s7, s6, 14
	s_add_i32 s7, s7, 0
	v_add_u32_e32 v68, s7, v183
	s_lshl_b32 s6, s6, 13
	s_waitcnt vmcnt(0)
	ds_write_b128 v68, v[98:101]
	v_add_u32_e32 v68, s7, v182
	s_add_i32 s7, s7, s6
	ds_write_b128 v68, v[102:105]
	v_add3_u32 v68, s7, v184, v185
	ds_write_b128 v68, v[106:109] offset:32768
	v_add3_u32 v68, s7, v186, v187
	ds_write_b128 v68, v[110:113] offset:32768
	v_add3_u32 v68, s7, v188, v189
	ds_write_b128 v68, v[134:137] offset:32768

; #define SLOAD(i, k0) do { sr_[i].vs0 = *reinterpret_cast<const bf16x8*>(&Vh[(long)((k0) + sr) * ldv + sc]); sr_[i].vs1 = *reinterpret_cast<const bf16x8*>(&Vh[(long)((k0) + 32 + sr) * ldv + sc]); \
;     _Pragma("unroll") for (int q_ = 0; q_ < KPT; ++q_) sr_[i].ks[q_] = *reinterpret_cast<const bf16x8*>(&Kh[(long)((k0) + krow[q_]) * ldk + kcol[q_]]); } while (0)
; template <int DQK, int MODE, int SDEPTH, int ldq, int ldk, int ldv, int ldo, int ldg> ...
;     ...
;       if (j + 1 < NT) SLOAD(0, (j + 1) * KVBLK);
.Lm1_A_exit:
	s_barrier
	s_branch .LBB0_837
.Lm1_B_entry:
	v_lshl_add_u64 v[224:225], s[26:27], 0, v[178:179]
	v_add_co_u32_e32 v226, vcc, 0x1c010000, v224
	s_nop 1
	v_addc_co_u32_e32 v227, vcc, 0, v225, vcc
	v_add_co_u32_e32 v224, vcc, 0x1c018000, v224
	s_nop 1
	v_addc_co_u32_e32 v225, vcc, 0, v225, vcc
	global_load_dwordx4 v[98:101], v[226:227], off
	global_load_dwordx4 v[102:105], v[224:225], off
	v_lshl_add_u64 v[224:225], s[26:27], 0, v[176:177]
	v_lshl_add_u64 v[226:227], s[26:27], 0, v[174:175]
	global_load_dwordx4 v[106:109], v[224:225], off
	global_load_dwordx4 v[110:113], v[226:227], off
	v_lshl_add_u64 v[224:225], s[26:27], 0, v[172:173]
	global_load_dwordx4 v[134:137], v[224:225], off
	v_lshl_add_u64 v[172:173], v[172:173], 0, s[8:9]
	v_lshl_add_u64 v[174:175], v[174:175], 0, s[8:9]
	v_lshl_add_u64 v[176:177], v[176:177], 0, s[8:9]
	v_lshl_add_u64 v[178:179], v[178:179], 0, s[16:17]
	s_barrier
	s_branch .Lm1_BX
.Lm1_BY:
	s_cmp_gt_u32 s41, 34
	s_cbranch_scc1 .Lm1_BY_nl
	v_lshl_add_u64 v[224:225], s[26:27], 0, v[178:179]
	v_add_co_u32_e32 v226, vcc, 0x1c010000, v224
	s_nop 1
	v_addc_co_u32_e32 v227, vcc, 0, v225, vcc
	v_add_co_u32_e32 v224, vcc, 0x1c018000, v224
	s_nop 1
	v_addc_co_u32_e32 v225, vcc, 0, v225, vcc
	global_load_dwordx4 v[98:101], v[226:227], off
	global_load_dwordx4 v[102:105], v[224:225], off
	v_lshl_add_u64 v[224:225], s[26:27], 0, v[176:177]
	v_lshl_add_u64 v[226:227], s[26:27], 0, v[174:175]
	global_load_dwordx4 v[106:109], v[224:225], off
	global_load_dwordx4 v[110:113], v[226:227], off
	v_lshl_add_u64 v[224:225], s[26:27], 0, v[172:173]
	global_load_dwordx4 v[134:137], v[224:225], off
	v_lshl_add_u64 v[172:173], v[172:173], 0, s[8:9]
	v_lshl_add_u64 v[174:175], v[174:175], 0, s[8:9]
	v_lshl_add_u64 v[176:177], v[176:177], 0, s[8:9]
	v_lshl_add_u64 v[178:179], v[178:179], 0, s[16:17]
; template <int D0> __device__ __forceinline__ void pv_one(f32x16& od, int vb, bf16x8 pa0, bf16x8 pa1, bf16x8 pa2, bf16x8 pa3) {
;   const s16x4 l0 = tr_read<v_rd_off(D0, 0, 0)>(vb), h0 = tr_read<v_rd_off(D0, 0, 1)>(vb), l1 = tr_read<v_rd_off(D0, 1, 0)>(vb), h1 = tr_read<v_rd_off(D0, 1, 1)>(vb);
;   const s16x4 l2 = tr_read<v_rd_off(D0, 2, 0)>(vb), h2 = tr_read<v_rd_off(D0, 2, 1)>(vb), l3 = tr_read<v_rd_off(D0, 3, 0)>(vb), h3 = tr_read<v_rd_off(D0, 3, 1)>(vb);
;   asm volatile("s_waitcnt lgkmcnt(0)" ::: "memory"); SBAR();
;     ...
;   od = __builtin_amdgcn_mfma_f32_32x32x16_bf16(pa0, PK(l0, h0), od, 0, 0, 0);
;   od = __builtin_amdgcn_mfma_f32_32x32x16_bf16(pa1, PK(l1, h1), od, 0, 0, 0);
;   od = __builtin_amdgcn_mfma_f32_32x32x16_bf16(pa2, PK(l2, h2), od, 0, 0, 0);
;   od = __builtin_amdgcn_mfma_f32_32x32x16_bf16(pa3, PK(l3, h3), od, 0, 0, 0);
;     ...
; }
; __device__ __forceinline__ void pv_d0(f32x16* o, int vb, bf16x8 pa0, bf16x8 pa1, bf16x8 pa2, bf16x8 pa3) {
;   pv_one<0>(o[0], vb, pa0, pa1, pa2, pa3); pv_one<1>(o[1], vb, pa0, pa1, pa2, pa3); pv_one<2>(o[2], vb, pa0, pa1, pa2, pa3); pv_one<3>(o[3], vb, pa0, pa1, pa2, pa3);
; }
; __device__ __forceinline__ void pack_p(const f32x16& p0, const f32x16& p1, bf16x8& pa0, bf16x8& pa1, bf16x8& pa2, bf16x8& pa3) {
;     ...
;   PK4(p0, 0, pa0); PK4(p0, 8, pa1); PK4(p1, 0, pa2); PK4(p1, 8, pa3);
;     ...
; }
; template <int DQK>
; __device__ __forceinline__ void partialSM(f32x16& p0, f32x16& p1, float& m_reg, float& mn, float& alpha) {
;   constexpr float SCALE = DQK == 128 ? 0.088388347648318440f : 0.072168783648703220f;
;   constexpr float C = SCALE * LOG2E;
;   float pmax = p0[0];
; #pragma unroll
;   for (int r = 1; r < 16; ++r) pmax = fmaxf(pmax, p0[r]);
; #pragma unroll
;   for (int r = 0; r < 16; ++r) pmax = fmaxf(pmax, p1[r]);
;   { auto rr = __builtin_amdgcn_permlane32_swap(__float_as_uint(pmax), __float_as_uint(pmax), false, false);
;     pmax = fmaxf(__uint_as_float(rr[0]), __uint_as_float(rr[1])); }
;   if (__builtin_expect(__all(pmax - m_reg <= THR / SCALE), 1)) { mn = m_reg; alpha = 1.f; }
;   else { mn = fmaxf(m_reg, pmax); alpha = __builtin_amdgcn_exp2f((m_reg - mn) * C); m_reg = mn; }
;   const float mnC = -mn * C;
; #pragma unroll
;   for (int r = 0; r < 16; ++r) p0[r] = fmaf(p0[r], C, mnC);
; #pragma unroll
;   for (int r = 0; r < 16; ++r) p1[r] = fmaf(p1[r], C, mnC);
; #pragma unroll
.Lm1_BY_nl:
	v_mul_f32_e32 v207, 0xbdd53b94, v205
	v_fmamk_f32 v82, v82, 0x3dd53b94, v207
	v_fmamk_f32 v83, v83, 0x3dd53b94, v207
	v_fmamk_f32 v84, v84, 0x3dd53b94, v207
	v_fmamk_f32 v85, v85, 0x3dd53b94, v207
	v_fmamk_f32 v86, v86, 0x3dd53b94, v207
	v_fmamk_f32 v87, v87, 0x3dd53b94, v207
	v_fmamk_f32 v88, v88, 0x3dd53b94, v207
	v_fmamk_f32 v89, v89, 0x3dd53b94, v207
	v_fmamk_f32 v90, v90, 0x3dd53b94, v207
	v_fmamk_f32 v91, v91, 0x3dd53b94, v207
	v_fmamk_f32 v92, v92, 0x3dd53b94, v207
	v_fmamk_f32 v93, v93, 0x3dd53b94, v207
	v_fmamk_f32 v94, v94, 0x3dd53b94, v207
	v_fmamk_f32 v95, v95, 0x3dd53b94, v207
	v_fmamk_f32 v96, v96, 0x3dd53b94, v207
	v_fmamk_f32 v97, v97, 0x3dd53b94, v207
	v_fmamk_f32 v66, v66, 0x3dd53b94, v207
	v_fmamk_f32 v67, v67, 0x3dd53b94, v207
	v_fmamk_f32 v68, v68, 0x3dd53b94, v207
	v_fmamk_f32 v69, v69, 0x3dd53b94, v207
	v_fmamk_f32 v70, v70, 0x3dd53b94, v207
	v_fmamk_f32 v71, v71, 0x3dd53b94, v207
	v_fmamk_f32 v72, v72, 0x3dd53b94, v207
	v_fmamk_f32 v73, v73, 0x3dd53b94, v207
	v_fmamk_f32 v74, v74, 0x3dd53b94, v207
	v_fmamk_f32 v75, v75, 0x3dd53b94, v207
	v_fmamk_f32 v76, v76, 0x3dd53b94, v207
	v_fmamk_f32 v77, v77, 0x3dd53b94, v207
	v_fmamk_f32 v78, v78, 0x3dd53b94, v207
	v_fmamk_f32 v79, v79, 0x3dd53b94, v207
	v_fmamk_f32 v80, v80, 0x3dd53b94, v207
	v_fmac_f32_e32 v207, 0x3dd53b94, v81
	v_exp_f32_e32 v81, v82
	v_exp_f32_e32 v82, v83
	v_exp_f32_e32 v83, v84
	v_exp_f32_e32 v84, v85
	v_exp_f32_e32 v85, v86
	v_exp_f32_e32 v86, v87
	v_exp_f32_e32 v87, v88
	v_exp_f32_e32 v88, v89
	v_exp_f32_e32 v89, v90
	v_exp_f32_e32 v90, v91
	v_exp_f32_e32 v91, v92
	v_exp_f32_e32 v92, v93
	v_exp_f32_e32 v93, v94
	v_exp_f32_e32 v94, v95
	v_exp_f32_e32 v95, v96
	v_exp_f32_e32 v96, v97
	v_exp_f32_e32 v97, v66
	v_add_f32_e32 v66, 0, v81
	v_add_f32_e32 v66, v82, v66
	v_add_f32_e32 v66, v83, v66
	v_add_f32_e32 v66, v84, v66
	v_add_f32_e32 v66, v85, v66
	v_add_f32_e32 v66, v86, v66
	v_add_f32_e32 v66, v87, v66
	v_add_f32_e32 v66, v88, v66
	v_add_f32_e32 v66, v89, v66
	v_add_f32_e32 v66, v90, v66
	v_add_f32_e32 v66, v91, v66
	v_add_f32_e32 v66, v92, v66
	v_add_f32_e32 v66, v93, v66
	v_exp_f32_e32 v208, v67
	v_add_f32_e32 v66, v94, v66
	v_exp_f32_e32 v209, v68
	v_add_f32_e32 v66, v95, v66
	v_exp_f32_e32 v210, v69
	v_add_f32_e32 v66, v96, v66
	v_exp_f32_e32 v211, v70
	v_add_f32_e32 v66, v97, v66
	v_exp_f32_e32 v212, v71
	v_add_f32_e32 v66, v208, v66
	v_exp_f32_e32 v213, v72
	v_add_f32_e32 v66, v209, v66
	v_exp_f32_e32 v214, v73
	v_add_f32_e32 v66, v210, v66
	v_exp_f32_e32 v215, v74
	v_add_f32_e32 v66, v211, v66
	v_exp_f32_e32 v216, v75
	v_add_f32_e32 v66, v212, v66
	v_exp_f32_e32 v217, v76
	v_add_f32_e32 v66, v213, v66
	v_exp_f32_e32 v218, v77
	v_add_f32_e32 v66, v214, v66
	v_exp_f32_e32 v219, v78
	v_add_f32_e32 v66, v215, v66
	v_exp_f32_e32 v220, v79
	v_add_f32_e32 v66, v216, v66
	v_exp_f32_e32 v221, v80
	v_add_f32_e32 v66, v217, v66
	v_exp_f32_e32 v207, v207
	v_add_f32_e32 v66, v218, v66
	v_add_f32_e32 v66, v219, v66
	v_add_f32_e32 v66, v220, v66
	v_add_f32_e32 v66, v221, v66
	v_add_f32_e32 v66, v207, v66
	v_mov_b32_e32 v67, v66
	s_nop 1
	v_permlane32_swap_b32_e32 v66, v67
	v_cvt_pk_bf16_f32 v68, v81, v82
	v_cvt_pk_bf16_f32 v69, v83, v84
	v_cvt_pk_bf16_f32 v70, v85, v86
	v_cvt_pk_bf16_f32 v71, v87, v88
	v_cvt_pk_bf16_f32 v72, v89, v90
	v_cvt_pk_bf16_f32 v73, v91, v92
	v_cvt_pk_bf16_f32 v74, v93, v94
	v_cvt_pk_bf16_f32 v75, v95, v96
	v_cvt_pk_bf16_f32 v76, v97, v208
	v_cvt_pk_bf16_f32 v77, v209, v210
	v_cvt_pk_bf16_f32 v78, v211, v212
	v_cvt_pk_bf16_f32 v79, v213, v214
	v_cvt_pk_bf16_f32 v80, v215, v216
	v_cvt_pk_bf16_f32 v81, v217, v218
	v_cvt_pk_bf16_f32 v82, v219, v220
	v_cvt_pk_bf16_f32 v83, v221, v207
	v_permlane32_swap_b32_e32 v68, v70
	v_permlane32_swap_b32_e32 v69, v71
	v_permlane32_swap_b32_e32 v72, v74
	v_permlane32_swap_b32_e32 v73, v75
	v_permlane32_swap_b32_e32 v76, v78
	v_permlane32_swap_b32_e32 v77, v79
	v_permlane32_swap_b32_e32 v80, v82
	v_permlane32_swap_b32_e32 v81, v83
	v_lshl_add_u32 v96, s42, 14, v204
	s_setprio 1
	ds_read_b64_tr_b16 v[84:85], v96 offset:0
	ds_read_b64_tr_b16 v[86:87], v96 offset:0x800
	ds_read_b64_tr_b16 v[88:89], v96 offset:0x1000
	ds_read_b64_tr_b16 v[90:91], v96 offset:0x1800
	ds_read_b64_tr_b16 v[92:93], v96 offset:0x2000
	ds_read_b64_tr_b16 v[94:95], v96 offset:0x2800
	ds_read_b64_tr_b16 v[208:209], v96 offset:0x3000
	ds_read_b64_tr_b16 v[210:211], v96 offset:0x3800
	s_waitcnt lgkmcnt(0)
	s_nop 0
	v_mfma_f32_32x32x16_bf16 v[2:17], v[68:71], v[84:87], v[2:17]
	ds_read_b64_tr_b16 v[84:85], v96 offset:0x200
	ds_read_b64_tr_b16 v[86:87], v96 offset:0xa00
	v_mfma_f32_32x32x16_bf16 v[2:17], v[72:75], v[88:91], v[2:17]
	ds_read_b64_tr_b16 v[88:89], v96 offset:0x1200
	ds_read_b64_tr_b16 v[90:91], v96 offset:0x1a00
	v_mfma_f32_32x32x16_bf16 v[2:17], v[76:79], v[92:95], v[2:17]
	ds_read_b64_tr_b16 v[92:93], v96 offset:0x2200
	ds_read_b64_tr_b16 v[94:95], v96 offset:0x2a00
	ds_read_b64_tr_b16 v[212:213], v96 offset:0x3200
	ds_read_b64_tr_b16 v[214:215], v96 offset:0x3a00
	s_waitcnt lgkmcnt(0)
	v_mfma_f32_32x32x16_bf16 v[2:17], v[80:83], v[208:211], v[2:17]
	v_mfma_f32_32x32x16_bf16 v[50:65], v[68:71], v[84:87], v[50:65]
	ds_read_b64_tr_b16 v[84:85], v96 offset:0x400
	ds_read_b64_tr_b16 v[86:87], v96 offset:0xc00
	v_mfma_f32_32x32x16_bf16 v[50:65], v[72:75], v[88:91], v[50:65]
	ds_read_b64_tr_b16 v[88:89], v96 offset:0x1400
	ds_read_b64_tr_b16 v[90:91], v96 offset:0x1c00
	v_mfma_f32_32x32x16_bf16 v[50:65], v[76:79], v[92:95], v[50:65]
	ds_read_b64_tr_b16 v[92:93], v96 offset:0x2400
	ds_read_b64_tr_b16 v[94:95], v96 offset:0x2c00
	ds_read_b64_tr_b16 v[208:209], v96 offset:0x3400
	ds_read_b64_tr_b16 v[210:211], v96 offset:0x3c00
	s_waitcnt lgkmcnt(0)
	v_mfma_f32_32x32x16_bf16 v[50:65], v[80:83], v[212:215], v[50:65]
	v_mfma_f32_32x32x16_bf16 v[34:49], v[68:71], v[84:87], v[34:49]
	ds_read_b64_tr_b16 v[84:85], v96 offset:0x600
	ds_read_b64_tr_b16 v[86:87], v96 offset:0xe00
	v_mfma_f32_32x32x16_bf16 v[34:49], v[72:75], v[88:91], v[34:49]
	ds_read_b64_tr_b16 v[88:89], v96 offset:0x1600
	ds_read_b64_tr_b16 v[90:91], v96 offset:0x1e00
	v_mfma_f32_32x32x16_bf16 v[34:49], v[76:79], v[92:95], v[34:49]
	ds_read_b64_tr_b16 v[92:93], v96 offset:0x2600
	ds_read_b64_tr_b16 v[94:95], v96 offset:0x2e00
	ds_read_b64_tr_b16 v[212:213], v96 offset:0x3600
	ds_read_b64_tr_b16 v[214:215], v96 offset:0x3e00
	s_waitcnt lgkmcnt(0)
	v_mfma_f32_32x32x16_bf16 v[34:49], v[80:83], v[208:211], v[34:49]
	v_mfma_f32_32x32x16_bf16 v[18:33], v[68:71], v[84:87], v[18:33]
	v_mfma_f32_32x32x16_bf16 v[18:33], v[72:75], v[88:91], v[18:33]
	v_mfma_f32_32x32x16_bf16 v[18:33], v[76:79], v[92:95], v[18:33]
	v_mfma_f32_32x32x16_bf16 v[18:33], v[80:83], v[212:215], v[18:33]
	s_setprio 0
	v_add_f32_e32 v66, v66, v67
	v_fmac_f32_e32 v66, v169, v206
	s_waitcnt lgkmcnt(0)
	v_mov_b32_e32 v169, v66
	s_barrier
	s_cmp_eq_u32 s41, 36
	s_cbranch_scc1 .LBB0_837

; #define SWRITE(b, i) do { *(bf16x8*)(V_lds + (b) * SH::V + vst0) = sr_[i].vs0; *(bf16x8*)(V_lds + (b) * SH::V + vst1) = sr_[i].vs1; \
;     _Pragma("unroll") for (int q_ = 0; q_ < KPT; ++q_) *(bf16x8*)(K_lds + (b) * SH::K + KSWZ(krow[q_], kcol[q_] * 2)) = sr_[i].ks[q_]; } while (0)
; template <int DQK>
; __device__ __forceinline__ void partialSM(f32x16& p0, f32x16& p1, float& m_reg, float& mn, float& alpha) {
;     ...
;   else { mn = fmaxf(m_reg, pmax); alpha = __builtin_amdgcn_exp2f((m_reg - mn) * C); m_reg = mn; }
; template <int DQK, int MODE, int SDEPTH, int ldq, int ldk, int ldv, int ldo, int ldg> ...
;     ...
;       if (j + 1 < NT) { asm volatile("s_waitcnt vmcnt(0)" ::: "memory"); SWRITE(bsel ^ 1, 0); }
;       __syncthreads();
.Lm1_B_833:
	v_cndmask_b32_e64 v205, v207, v205, s[6:7]
	s_cmp_gt_u32 s41, 34
	s_cbranch_scc1 .Lm1_BX_nw
	s_xor_b32 s44, s42, 1
	s_lshl_b32 s45, s44, 14
	s_add_i32 s45, s45, 0
	v_add_u32_e32 v224, s45, v183
	s_lshl_b32 s44, s44, 13
	s_waitcnt vmcnt(0)
	ds_write_b128 v224, v[98:101]
	v_add_u32_e32 v224, s45, v182
	s_add_i32 s45, s45, s44
	ds_write_b128 v224, v[102:105]
	v_add3_u32 v224, s45, v184, v185
	ds_write_b128 v224, v[106:109] offset:32768
	v_add3_u32 v224, s45, v186, v187
	ds_write_b128 v224, v[110:113] offset:32768
	v_add3_u32 v224, s45, v188, v189
	ds_write_b128 v224, v[134:137] offset:32768
.Lm1_BX_nw:
	s_waitcnt lgkmcnt(0)
	s_barrier
	s_add_i32 s41, s41, 1
	s_branch .Lm1_BY

; __device__ __forceinline__ int v_st(int k, int c) { const int kk = (k & ~0xC) | ((k & 4) << 1) | ((k & 8) >> 1); return ((kk >> 3) * 4 + (c >> 5)) * 512 + ((kk & 7) * 32 + (c & 31)) * 2; }
; __device__ __forceinline__ int v_rd_base(int lane) { return ((lane & 3) << 3) | (((lane >> 2) & 3) << 6) | (((lane >> 4) & 1) << 5) | (((lane >> 5) & 1) << 8); }
; template <int DQK, int MODE, int SDEPTH, int ldq, int ldk, int ldv, int ldo, int ldg> ...
;     ...
;   int tid_ = threadIdx.x; asm volatile("" : "+v"(tid_));
;   const int tid = tid_, wid = tid >> 6, lane = tid & 63, r32 = lane & 31, hi = lane >> 5;
;   char* V_lds = lds; char* K_lds = lds + 2 * SH::V;
;   float* ws = (float*)(lds + SH::WSO) + wid * 64; float* li_l = ws; float* al_l = ws + 32;
;   float m_reg = -1e30f, l_reg = 0; f32x16 o[4] = {}; bf16x8 qr[ND];
;   const bf16_t* Qw = Qb + (long)(wid * QBLK + r32) * ldq + hi * 8;
; #pragma unroll
;   for (int d0 = 0; d0 < ND; ++d0) qr[d0] = *reinterpret_cast<const bf16x8*>(Qw + d0 * 16);
;   const int sr = tid >> 4, sc = (tid & 15) * 8, vst0 = v_st(sr, sc), vst1 = v_st(32 + sr, sc);
;   int krow[KPT], kcol[KPT];
; #pragma unroll
;   for (int i = 0; i < KPT; ++i) { const int id = tid + 512 * i; krow[i] = id / NKC; kcol[i] = (id % NKC) * 8; }
;   const int vb0 = (int)(uintptr_t)V_lds + v_rd_base(lane);
;   struct { bf16x8 vs0, vs1, ks[KPT]; } sr_[SDEPTH == 0 ? 1 : SDEPTH];
;   constexpr int SE = 0, SO = SDEPTH == 2 ? 1 : 0;
; template <int ph> __device__ __forceinline__ void run_phase(const MArgs& a, unsigned char* lds, int tid, int lane, int wave, int G, int bx, int vcu) {
;     ...
;     { const int u = vcu + 256, bh = u >> 3, qb = u & 7, b = bh >> 2, h = bh & 3; const size_t r0 = (size_t)b * RB + NCTX + 256 * qb;
;       att::attn_unit<192, 0, 0, 768, 768, 512, 1024, 0>(Q + r0 * 768 + 192 * h, Kb + (size_t)b * RB * 768 + 192 * h, Vb + (size_t)b * RB * 512 + 128 * h, CAT + r0 * 1024 + 512 + 128 * h, RB, (char*)lds, 0, 0.f, 0.f, nullptr); }
.LBB0_894:
	s_or_b64 exec, exec, s[4:5]
	s_add_i32 s3, s92, 0x100
	s_ashr_i32 s18, s3, 5
	s_mul_i32 s4, s18, 0x900
	s_mul_hi_i32 s3, s18, 0x900
	s_add_u32 s14, s4, s38
	s_addc_u32 s15, s3, 0
	s_mul_i32 s3, s15, 0x600
	s_mul_hi_u32 s4, s14, 0x600
	s_add_i32 s4, s4, s3
	s_mul_i32 s3, s14, 0x600
	s_add_u32 s3, s35, s3
	s_addc_u32 s5, s36, s4
	s_lshl_b32 s16, s39, 1
	s_add_u32 s4, s3, s16
	s_addc_u32 s5, s5, 0
	s_mul_i32 s6, s18, 0x360000
	s_mul_hi_i32 s7, s18, 0x360000
	s_add_u32 s3, s30, s6
	s_addc_u32 s17, s34, s7
	s_add_u32 s16, s3, s16
	s_addc_u32 s17, s17, 0
	s_mul_i32 s38, s18, 0x240000
	s_mul_hi_i32 s3, s18, 0x240000
	s_add_u32 s38, s28, s38
	s_addc_u32 s3, s29, s3
	s_add_u32 s38, s38, s40
	s_addc_u32 s39, s3, 0
	v_mov_b32_e32 v20, v0
	s_mov_b32 s3, 0x2aaaaaab
	v_mov_b32_e32 v169, 0
	s_waitcnt lgkmcnt(1)
	v_mul_hi_i32 v1, v20, s3
	v_lshrrev_b32_e32 v3, 31, v1
	v_ashrrev_i32_e32 v1, 2, v1
	v_add_u32_e32 v22, v1, v3
	v_mul_lo_u32 v1, v22, 24
	v_sub_u32_e32 v23, v20, v1
	v_add_u32_e32 v1, 0x200, v20
	v_mul_hi_i32 v3, v1, s3
	v_lshrrev_b32_e32 v5, 31, v3
	v_ashrrev_i32_e32 v3, 2, v3
	v_add_u32_e32 v24, v3, v5
	v_mul_lo_u32 v3, v24, 24
	v_sub_u32_e32 v25, v1, v3
	v_add_u32_e32 v1, 0x400, v20
	v_mul_hi_i32 v3, v1, s3
	v_lshrrev_b32_e32 v5, 31, v3
	v_ashrrev_i32_e32 v3, 2, v3
	v_add_u32_e32 v26, v3, v5
	v_ashrrev_i32_e32 v2, 4, v20
	v_mul_lo_u32 v3, v26, 24
	v_lshlrev_b32_e32 v21, 3, v20
	v_add_u32_e32 v4, 32, v2
	v_sub_u32_e32 v27, v1, v3
	v_ashrrev_i32_e32 v3, 31, v2
	v_and_b32_e32 v166, 0x78, v21
	v_lshlrev_b64 v[12:13], 10, v[2:3]
	v_ashrrev_i32_e32 v5, 31, v4
	v_lshl_add_u64 v[14:15], s[38:39], 0, v[12:13]
	v_lshlrev_b32_e32 v16, 1, v166
	v_mov_b32_e32 v17, v169
	v_lshlrev_b64 v[18:19], 10, v[4:5]
	v_lshlrev_b32_e32 v6, 3, v23
	v_lshl_add_u64 v[14:15], v[14:15], 0, v[16:17]
	v_lshl_add_u64 v[18:19], s[38:39], 0, v[18:19]
	s_movk_i32 s19, 0x600
	v_lshl_add_u64 v[16:17], v[18:19], 0, v[16:17]
	global_load_dwordx4 v[98:101], v[14:15], off
	global_load_dwordx4 v[102:105], v[16:17], off
	v_ashrrev_i32_e32 v7, 31, v6
	v_mov_b64_e32 v[14:15], s[16:17]
	v_mad_i64_i32 v[16:17], s[16:17], v22, s19, v[14:15]
	v_lshlrev_b64 v[6:7], 1, v[6:7]
	v_lshlrev_b32_e32 v8, 3, v25
	v_lshl_add_u64 v[16:17], v[16:17], 0, v[6:7]
	v_lshlrev_b32_e32 v10, 3, v27
	global_load_dwordx4 v[106:109], v[16:17], off
	v_ashrrev_i32_e32 v9, 31, v8
	v_mad_i64_i32 v[16:17], s[16:17], v24, s19, v[14:15]
	v_lshlrev_b64 v[8:9], 1, v[8:9]
	v_ashrrev_i32_e32 v11, 31, v10
	v_lshl_add_u64 v[16:17], v[16:17], 0, v[8:9]
	v_mad_i64_i32 v[14:15], s[16:17], v26, s19, v[14:15]
	v_lshlrev_b64 v[10:11], 1, v[10:11]
	v_ashrrev_i32_e32 v167, 6, v20
	global_load_dwordx4 v[110:113], v[16:17], off
	v_lshl_add_u64 v[14:15], v[14:15], 0, v[10:11]
	v_and_b32_e32 v180, 31, v20
	v_and_b32_e32 v3, 0x3fffffc0, v20
	v_lshlrev_b32_e32 v170, 5, v167
	global_load_dwordx4 v[142:145], v[14:15], off
	v_bfe_u32 v181, v20, 5, 1
	v_lshl_add_u32 v171, v3, 2, s31
	v_or_b32_e32 v3, v170, v180
	v_mov_b64_e32 v[14:15], s[4:5]
	v_mad_i64_i32 v[14:15], s[4:5], v3, s19, v[14:15]
	v_lshlrev_b32_e32 v168, 4, v181
	v_lshl_add_u64 v[14:15], v[14:15], 0, v[168:169]
	global_load_dwordx4 v[114:117], v[14:15], off
	global_load_dwordx4 v[118:121], v[14:15], off offset:32
	global_load_dwordx4 v[122:125], v[14:15], off offset:64
	global_load_dwordx4 v[126:129], v[14:15], off offset:96
	global_load_dwordx4 v[130:133], v[14:15], off offset:128
	global_load_dwordx4 v[134:137], v[14:15], off offset:160
	global_load_dwordx4 v[138:141], v[14:15], off offset:192
	global_load_dwordx4 v[146:149], v[14:15], off offset:224
	global_load_dwordx4 v[150:153], v[14:15], off offset:256
	global_load_dwordx4 v[154:157], v[14:15], off offset:288
	global_load_dwordx4 v[158:161], v[14:15], off offset:320
	global_load_dwordx4 v[162:165], v[14:15], off offset:352
	v_and_b32_e32 v3, 0xfffff0, v2
	v_lshlrev_b32_e32 v5, 1, v2
	v_and_or_b32 v3, v5, 8, v3
	v_lshrrev_b32_e32 v5, 1, v2
	v_and_b32_e32 v2, 3, v2
	v_and_or_b32 v2, v5, 4, v2
	v_and_b32_e32 v5, 0xfffff0, v4
	v_lshlrev_b32_e32 v4, 1, v4
	v_lshrrev_b32_e32 v3, 1, v3
	v_bfe_u32 v14, v21, 5, 2
	v_and_or_b32 v4, v4, 8, v5
	v_or_b32_e32 v3, v3, v14
	v_lshrrev_b32_e32 v4, 1, v4
	v_lshlrev_b32_e32 v5, 4, v20
	v_lshlrev_b32_e32 v3, 9, v3
	v_lshlrev_b32_e32 v2, 6, v2
	v_or_b32_e32 v4, v4, v14
	v_and_b32_e32 v14, 48, v5
	v_lshlrev_b32_e32 v4, 9, v4
	v_or3_b32 v183, v3, v2, v14
	v_or3_b32 v182, v4, v2, v14
	v_add_u32_e32 v2, 0, v183
	s_waitcnt vmcnt(0)
; __device__ __forceinline__ int v_st(int k, int c) { const int kk = (k & ~0xC) | ((k & 4) << 1) | ((k & 8) >> 1); return ((kk >> 3) * 4 + (c >> 5)) * 512 + ((kk & 7) * 32 + (c & 31)) * 2; }
; __device__ __forceinline__ int v_rd_base(int lane) { return ((lane & 3) << 3) | (((lane >> 2) & 3) << 6) | (((lane >> 4) & 1) << 5) | (((lane >> 5) & 1) << 8); }
; #define SLOAD(i, k0) do { sr_[i].vs0 = *reinterpret_cast<const bf16x8*>(&Vh[(long)((k0) + sr) * ldv + sc]); sr_[i].vs1 = *reinterpret_cast<const bf16x8*>(&Vh[(long)((k0) + 32 + sr) * ldv + sc]); \
;     _Pragma("unroll") for (int q_ = 0; q_ < KPT; ++q_) sr_[i].ks[q_] = *reinterpret_cast<const bf16x8*>(&Kh[(long)((k0) + krow[q_]) * ldk + kcol[q_]]); } while (0)
; #define SWRITE(b, i) do { *(bf16x8*)(V_lds + (b) * SH::V + vst0) = sr_[i].vs0; *(bf16x8*)(V_lds + (b) * SH::V + vst1) = sr_[i].vs1; \
;     _Pragma("unroll") for (int q_ = 0; q_ < KPT; ++q_) *(bf16x8*)(K_lds + (b) * SH::K + KSWZ(krow[q_], kcol[q_] * 2)) = sr_[i].ks[q_]; } while (0)
; template <int DQK, int MODE, int SDEPTH, int ldq, int ldk, int ldv, int ldo, int ldg> ...
;     ...
;   float m_reg = -1e30f, l_reg = 0; f32x16 o[4] = {}; bf16x8 qr[ND];
;   const bf16_t* Qw = Qb + (long)(wid * QBLK + r32) * ldq + hi * 8;
; #pragma unroll
;   for (int d0 = 0; d0 < ND; ++d0) qr[d0] = *reinterpret_cast<const bf16x8*>(Qw + d0 * 16);
;   const int sr = tid >> 4, sc = (tid & 15) * 8, vst0 = v_st(sr, sc), vst1 = v_st(32 + sr, sc);
;   int krow[KPT], kcol[KPT];
; #pragma unroll
;   for (int i = 0; i < KPT; ++i) { const int id = tid + 512 * i; krow[i] = id / NKC; kcol[i] = (id % NKC) * 8; }
;   const int vb0 = (int)(uintptr_t)V_lds + v_rd_base(lane);
;   struct { bf16x8 vs0, vs1, ks[KPT]; } sr_[SDEPTH == 0 ? 1 : SDEPTH];
;   constexpr int SE = 0, SO = SDEPTH == 2 ? 1 : 0;
;     ...
;   const int qb4 = n0 >> 6;
;   const float nlane = (float)(n0 + wid * QBLK + r32 - 4 * hi);
;     ...
;   f32x16 pA0, pA1, pB0, pB1; float mnA = 0.f, mnB = 0.f, alA = 1.f, alB = 1.f; bf16x8 pa0, pa1, pa2, pa3; const int NT = seq / KVBLK;
;   if constexpr (SDEPTH == 0) {
;     SLOAD(0, 0); asm volatile("s_waitcnt vmcnt(0)" ::: "memory"); SWRITE(0, 0); __syncthreads();
	s_movk_i32 s17, 0x180
	v_mul_lo_u32 v184, v22, s17
	s_movk_i32 s16, 0x100
	v_mul_lo_u32 v186, v24, s17
	v_and_b32_e32 v4, 0x70, v5
	v_bitop3_b32 v200, v168, v4, s16 bitop3:0x36
	s_movk_i32 s16, 0x120
	v_bitop3_b32 v201, v168, v4, s16 bitop3:0x36
	s_movk_i32 s16, 0x140
	v_mul_lo_u32 v188, v26, s17
	v_lshlrev_b32_e32 v3, 1, v20
	v_mad_u32_u24 v191, v180, s17, 0
	s_movk_i32 s17, 0x60
	v_bitop3_b32 v202, v168, v4, s16 bitop3:0x36
	s_movk_i32 s16, 0x160
	v_and_b32_e32 v3, 32, v3
	v_bitop3_b32 v195, v168, v4, s17 bitop3:0x36
	s_movk_i32 s17, 0x80
	v_bitop3_b32 v203, v168, v4, s16 bitop3:0x36
	s_movk_i32 s16, 0x118
	s_cmp_lg_u32 0, -1
	s_waitcnt vmcnt(16)
	ds_write_b128 v2, v[98:101]
	v_add_u32_e32 v2, 0, v182
	s_waitcnt vmcnt(15)
	ds_write_b128 v2, v[102:105]
	v_bitop3_b32 v2, v22, v23, 7 bitop3:0x6c
	v_lshlrev_b32_e32 v185, 4, v2
	v_add3_u32 v2, 0, v184, v185
	v_bitop3_b32 v196, v168, v4, s17 bitop3:0x36
	s_movk_i32 s17, 0xa0
	v_and_or_b32 v3, v21, s16, v3
	s_cselect_b32 s16, 0, 0
	s_waitcnt vmcnt(14)
	ds_write_b128 v2, v[106:109] offset:32768
	v_bitop3_b32 v2, v24, v25, 7 bitop3:0x6c
	v_lshlrev_b32_e32 v187, 4, v2
	v_add3_u32 v2, 0, v186, v187
	s_or_b64 s[6:7], s[12:13], s[6:7]
	s_movk_i32 s38, 0xc0
	s_movk_i32 s39, 0x70
	v_bitop3_b32 v197, v168, v4, s17 bitop3:0x36
	s_movk_i32 s17, 0xe0
	v_bitop3_b32 v192, v168, v5, s39 bitop3:0x78
	v_bitop3_b32 v193, v168, v4, 32 bitop3:0x36
	s_waitcnt vmcnt(13)
	ds_write_b128 v2, v[110:113] offset:32768
	v_bitop3_b32 v2, v26, v27, 7 bitop3:0x6c
	v_lshlrev_b32_e32 v189, 4, v2
	v_add3_u32 v2, 0, v188, v189
	v_bitop3_b32 v194, v168, v4, 64 bitop3:0x36
	s_waitcnt vmcnt(12)
	ds_write_b128 v2, v[142:145] offset:32768
	v_and_b32_e32 v2, 0xc0, v5
	v_add3_u32 v204, v2, s16, v3
	v_mov_b64_e32 v[2:3], s[6:7]
	v_bitop3_b32 v198, v168, v4, s38 bitop3:0x36
	v_bitop3_b32 v199, v168, v4, s17 bitop3:0x36
	v_mad_i64_i32 v[4:5], s[6:7], v26, s19, v[2:3]
	v_lshl_add_u64 v[4:5], v[4:5], 0, v[10:11]
	s_mov_b64 s[6:7], 0x18a18000
	v_lshl_add_u64 v[172:173], v[4:5], 0, s[6:7]
	v_mad_i64_i32 v[4:5], s[12:13], v24, s19, v[2:3]
	v_mad_i64_i32 v[2:3], s[12:13], v22, s19, v[2:3]
	v_lshl_add_u64 v[2:3], v[2:3], 0, v[6:7]
	v_lshl_add_u64 v[4:5], v[4:5], 0, v[8:9]
	v_lshl_add_u64 v[176:177], v[2:3], 0, s[6:7]
	v_mov_b32_e32 v2, 0x240000
	v_lshl_add_u64 v[174:175], v[4:5], 0, s[6:7]
	v_mad_i64_i32 v[2:3], s[6:7], s18, v2, v[12:13]
	v_and_b32_e32 v4, 15, v20
	v_or_b32_e32 v2, s37, v2
	v_lshlrev_b32_e32 v4, 4, v4
	v_mov_b32_e32 v5, v169
	v_mov_b32_e32 v16, v169
	v_mov_b32_e32 v17, v169
	v_and_b32_e32 v1, 63, v20
	v_lshl_add_u64 v[178:179], v[2:3], 0, v[4:5]
	v_mov_b32_e32 v2, v169
	v_mov_b32_e32 v3, v169
	v_mov_b32_e32 v4, v169
	v_mov_b32_e32 v6, v169
	v_mov_b32_e32 v7, v169
	v_mov_b32_e32 v8, v169
	v_mov_b32_e32 v9, v169
	v_mov_b32_e32 v10, v169
	v_mov_b32_e32 v11, v169
	v_mov_b32_e32 v12, v169
	v_mov_b32_e32 v13, v169
	v_mov_b32_e32 v14, v169
	v_mov_b32_e32 v15, v169
	v_mov_b64_e32 v[64:65], v[16:17]
	v_mov_b64_e32 v[48:49], v[16:17]
	v_mov_b64_e32 v[32:33], v[16:17]
	s_mov_b32 s3, 0
	v_cmp_gt_u32_e64 s[4:5], 32, v1
	v_lshl_add_u32 v190, v180, 2, v171
	v_mov_b32_e32 v205, 0xf149f2ca
	s_mov_b32 s37, 0x42ddb3d8
	s_mov_b64 s[12:13], 0x18000
	s_mov_b64 s[16:17], 0x10000
	v_mov_b64_e32 v[62:63], v[14:15]
	v_mov_b64_e32 v[60:61], v[12:13]
	v_mov_b64_e32 v[58:59], v[10:11]
	v_mov_b64_e32 v[56:57], v[8:9]
	v_mov_b64_e32 v[54:55], v[6:7]
	v_mov_b64_e32 v[52:53], v[4:5]
	v_mov_b64_e32 v[50:51], v[2:3]
	v_mov_b64_e32 v[46:47], v[14:15]
	v_mov_b64_e32 v[44:45], v[12:13]
	v_mov_b64_e32 v[42:43], v[10:11]
	v_mov_b64_e32 v[40:41], v[8:9]
	v_mov_b64_e32 v[38:39], v[6:7]
	v_mov_b64_e32 v[36:37], v[4:5]
	v_mov_b64_e32 v[34:35], v[2:3]
	v_mov_b64_e32 v[30:31], v[14:15]
	v_mov_b64_e32 v[28:29], v[12:13]
	v_mov_b64_e32 v[26:27], v[10:11]
	v_mov_b64_e32 v[24:25], v[8:9]
	v_mov_b64_e32 v[22:23], v[6:7]
	v_mov_b64_e32 v[20:21], v[4:5]
	v_mov_b64_e32 v[18:19], v[2:3]
	s_waitcnt lgkmcnt(0)
	s_barrier
	s_cmp_ge_u32 s93, 4
	s_cbranch_scc1 .Lm2_B_entry
	s_cmp_lt_u32 s3, 35
	s_cselect_b64 s[18:19], -1, 0
	s_cmp_gt_u32 s3, 34
	s_cbranch_scc1 .LBB0_896

; template <int DQK>
; __device__ __forceinline__ void partialSM(f32x16& p0, f32x16& p1, float& m_reg, float& mn, float& alpha) {
;     ...
;   float pmax = p0[0];
; #pragma unroll
;   for (int r = 1; r < 16; ++r) pmax = fmaxf(pmax, p0[r]);
; #pragma unroll
;   for (int r = 0; r < 16; ++r) pmax = fmaxf(pmax, p1[r]);
;   { auto rr = __builtin_amdgcn_permlane32_swap(__float_as_uint(pmax), __float_as_uint(pmax), false, false);
;     pmax = fmaxf(__uint_as_float(rr[0]), __uint_as_float(rr[1])); }
;   if (__builtin_expect(__all(pmax - m_reg <= THR / SCALE), 1)) { mn = m_reg; alpha = 1.f; }
;   else { mn = fmaxf(m_reg, pmax); alpha = __builtin_amdgcn_exp2f((m_reg - mn) * C); m_reg = mn; }
.LBB0_896:
	s_setprio 1
	s_and_b32 s38, s3, 1
	s_mul_i32 s6, s38, 0x6000
	v_add_u32_e32 v222, s6, v191
	v_add_u32_e32 v223, v222, v192
	ds_read_b128 v[206:209], v223 offset:32768
	ds_read_b128 v[210:213], v223 offset:45056
	v_add_u32_e32 v223, v222, v193
	ds_read_b128 v[214:217], v223 offset:32768
	ds_read_b128 v[218:221], v223 offset:45056
	v_add_u32_e32 v223, v222, v194
	ds_read_b128 v[228:231], v223 offset:32768
	ds_read_b128 v[232:235], v223 offset:45056
	v_add_u32_e32 v223, v222, v195
	ds_read_b128 v[236:239], v223 offset:32768
	ds_read_b128 v[240:243], v223 offset:45056
	v_add_u32_e32 v223, v222, v196
	ds_read_b128 v[244:247], v223 offset:32768
	ds_read_b128 v[248:251], v223 offset:45056
	s_waitcnt lgkmcnt(9)
	v_mfma_f32_32x32x16_bf16 v[82:97], v[206:209], v[114:117], 0
	s_waitcnt lgkmcnt(8)
	v_mfma_f32_32x32x16_bf16 v[66:81], v[210:213], v[114:117], 0
	v_add_u32_e32 v223, v222, v197
	ds_read_b128 v[206:209], v223 offset:32768
	ds_read_b128 v[210:213], v223 offset:45056
	s_waitcnt lgkmcnt(9)
	v_mfma_f32_32x32x16_bf16 v[82:97], v[214:217], v[118:121], v[82:97]
	s_waitcnt lgkmcnt(8)
	v_mfma_f32_32x32x16_bf16 v[66:81], v[218:221], v[118:121], v[66:81]
	v_add_u32_e32 v223, v222, v198
	ds_read_b128 v[214:217], v223 offset:32768
	ds_read_b128 v[218:221], v223 offset:45056
	s_waitcnt lgkmcnt(9)
	v_mfma_f32_32x32x16_bf16 v[82:97], v[228:231], v[122:125], v[82:97]
	s_waitcnt lgkmcnt(8)
	v_mfma_f32_32x32x16_bf16 v[66:81], v[232:235], v[122:125], v[66:81]
	v_add_u32_e32 v223, v222, v199
	ds_read_b128 v[228:231], v223 offset:32768
	ds_read_b128 v[232:235], v223 offset:45056
	s_waitcnt lgkmcnt(9)
	v_mfma_f32_32x32x16_bf16 v[82:97], v[236:239], v[126:129], v[82:97]
	s_waitcnt lgkmcnt(8)
	v_mfma_f32_32x32x16_bf16 v[66:81], v[240:243], v[126:129], v[66:81]
	v_add_u32_e32 v223, v222, v200
	ds_read_b128 v[236:239], v223 offset:32768
	ds_read_b128 v[240:243], v223 offset:45056
	s_waitcnt lgkmcnt(9)
	v_mfma_f32_32x32x16_bf16 v[82:97], v[244:247], v[130:133], v[82:97]
	s_waitcnt lgkmcnt(8)
	v_mfma_f32_32x32x16_bf16 v[66:81], v[248:251], v[130:133], v[66:81]
	v_add_u32_e32 v223, v222, v201
	ds_read_b128 v[244:247], v223 offset:32768
	ds_read_b128 v[248:251], v223 offset:45056
	s_waitcnt lgkmcnt(9)
	v_mfma_f32_32x32x16_bf16 v[82:97], v[206:209], v[134:137], v[82:97]
	s_waitcnt lgkmcnt(8)
	v_mfma_f32_32x32x16_bf16 v[66:81], v[210:213], v[134:137], v[66:81]
	v_add_u32_e32 v223, v222, v202
	ds_read_b128 v[206:209], v223 offset:32768
	ds_read_b128 v[210:213], v223 offset:45056
	s_waitcnt lgkmcnt(9)
	v_mfma_f32_32x32x16_bf16 v[82:97], v[214:217], v[138:141], v[82:97]
	s_waitcnt lgkmcnt(8)
	v_mfma_f32_32x32x16_bf16 v[66:81], v[218:221], v[138:141], v[66:81]
	v_add_u32_e32 v223, v222, v203
	ds_read_b128 v[214:217], v223 offset:32768
	ds_read_b128 v[218:221], v223 offset:45056
	s_waitcnt lgkmcnt(9)
	v_mfma_f32_32x32x16_bf16 v[82:97], v[228:231], v[146:149], v[82:97]
	s_waitcnt lgkmcnt(8)
	v_mfma_f32_32x32x16_bf16 v[66:81], v[232:235], v[146:149], v[66:81]
	s_waitcnt lgkmcnt(7)
	v_mfma_f32_32x32x16_bf16 v[82:97], v[236:239], v[150:153], v[82:97]
	s_waitcnt lgkmcnt(6)
	v_mfma_f32_32x32x16_bf16 v[66:81], v[240:243], v[150:153], v[66:81]
	s_waitcnt lgkmcnt(5)
	v_mfma_f32_32x32x16_bf16 v[82:97], v[244:247], v[154:157], v[82:97]
	s_waitcnt lgkmcnt(4)
	v_mfma_f32_32x32x16_bf16 v[66:81], v[248:251], v[154:157], v[66:81]
	s_waitcnt lgkmcnt(3)
	v_mfma_f32_32x32x16_bf16 v[82:97], v[206:209], v[158:161], v[82:97]
	s_waitcnt lgkmcnt(2)
	v_mfma_f32_32x32x16_bf16 v[66:81], v[210:213], v[158:161], v[66:81]
	s_waitcnt lgkmcnt(1)
	v_mfma_f32_32x32x16_bf16 v[82:97], v[214:217], v[162:165], v[82:97]
	s_waitcnt lgkmcnt(0)
	v_mfma_f32_32x32x16_bf16 v[66:81], v[218:221], v[162:165], v[66:81]
	s_setprio 0
	s_nop 10
	v_max_f32_e32 v206, v83, v83
	v_max_f32_e32 v207, v82, v82
	v_max_f32_e32 v206, v207, v206
	v_max3_f32 v206, v206, v84, v85
	v_max3_f32 v206, v206, v86, v87
	v_max3_f32 v206, v206, v88, v89
	v_max3_f32 v206, v206, v90, v91
	v_max3_f32 v206, v206, v92, v93
	v_max3_f32 v206, v206, v94, v95
	v_max3_f32 v206, v206, v96, v97
	v_max3_f32 v206, v206, v66, v67
	v_max3_f32 v206, v206, v68, v69
	v_max3_f32 v206, v206, v70, v71
	v_max3_f32 v206, v206, v72, v73
	v_max3_f32 v206, v206, v74, v75
	v_max3_f32 v206, v206, v76, v77
	v_max3_f32 v206, v206, v78, v79
	v_max3_f32 v206, v206, v80, v81
	v_mov_b32_e32 v207, v206
	s_nop 1
	v_permlane32_swap_b32_e32 v206, v207
	v_max_f32_e32 v207, v207, v207
	v_max_f32_e32 v206, v206, v206
	v_max_f32_e32 v206, v206, v207
	v_max_f32_e32 v207, v205, v205
	v_max_f32_e32 v207, v207, v206
	v_sub_f32_e32 v208, v206, v205
	v_sub_f32_e32 v206, v205, v207
	v_mul_f32_e32 v206, 0x3dd53b94, v206
	v_exp_f32_e32 v206, v206
	v_cmp_ge_f32_e32 vcc, s37, v208
	s_cmp_eq_u64 vcc, exec
	s_cselect_b64 s[6:7], -1, 0
	v_cndmask_b32_e64 v206, v206, 1.0, s[6:7]
	v_cmp_gt_f32_e32 vcc, 1.0, v206
	s_cbranch_vccz .LBB0_900
	s_and_saveexec_b64 s[54:55], s[4:5]
	ds_write_b32 v190, v206 offset:128
	s_or_b64 exec, exec, s[54:55]
	s_waitcnt lgkmcnt(0)
	v_add_u32_e32 v220, v171, v168
	ds_read_b128 v[208:211], v220 offset:224
	ds_read_b128 v[212:215], v220 offset:192
	ds_read_b128 v[216:219], v220 offset:160
	ds_read_b128 v[220:223], v220 offset:128
	s_waitcnt lgkmcnt(3)
	v_pk_mul_f32 v[14:15], v[14:15], v[208:209]
	s_waitcnt lgkmcnt(2)
	v_pk_mul_f32 v[10:11], v[10:11], v[212:213]
	s_waitcnt lgkmcnt(1)
	v_pk_mul_f32 v[6:7], v[6:7], v[216:217]
	v_pk_mul_f32 v[16:17], v[16:17], v[210:211]
	v_pk_mul_f32 v[12:13], v[12:13], v[214:215]
	v_pk_mul_f32 v[8:9], v[8:9], v[218:219]
	s_waitcnt lgkmcnt(0)
	v_pk_mul_f32 v[4:5], v[4:5], v[222:223]
	v_pk_mul_f32 v[2:3], v[2:3], v[220:221]
	v_pk_mul_f32 v[62:63], v[62:63], v[208:209]
	v_pk_mul_f32 v[58:59], v[58:59], v[212:213]
	v_pk_mul_f32 v[54:55], v[54:55], v[216:217]
	v_pk_mul_f32 v[64:65], v[64:65], v[210:211]
	v_pk_mul_f32 v[60:61], v[60:61], v[214:215]
	v_pk_mul_f32 v[56:57], v[56:57], v[218:219]
	v_pk_mul_f32 v[52:53], v[52:53], v[222:223]
	v_pk_mul_f32 v[50:51], v[50:51], v[220:221]
	v_pk_mul_f32 v[46:47], v[46:47], v[208:209]
	v_pk_mul_f32 v[42:43], v[42:43], v[212:213]
	v_pk_mul_f32 v[38:39], v[38:39], v[216:217]
	v_pk_mul_f32 v[48:49], v[48:49], v[210:211]
	v_pk_mul_f32 v[44:45], v[44:45], v[214:215]
	v_pk_mul_f32 v[40:41], v[40:41], v[218:219]
	v_pk_mul_f32 v[36:37], v[36:37], v[222:223]
	v_pk_mul_f32 v[34:35], v[34:35], v[220:221]
	v_pk_mul_f32 v[30:31], v[30:31], v[208:209]
	v_pk_mul_f32 v[26:27], v[26:27], v[212:213]
	v_pk_mul_f32 v[22:23], v[22:23], v[216:217]
	v_pk_mul_f32 v[32:33], v[32:33], v[210:211]
	v_pk_mul_f32 v[28:29], v[28:29], v[214:215]
	v_pk_mul_f32 v[24:25], v[24:25], v[218:219]
	v_pk_mul_f32 v[20:21], v[20:21], v[222:223]
	v_pk_mul_f32 v[18:19], v[18:19], v[220:221]
; template <int D0> __device__ __forceinline__ void pv_one(f32x16& od, int vb, bf16x8 pa0, bf16x8 pa1, bf16x8 pa2, bf16x8 pa3) {
;   const s16x4 l0 = tr_read<v_rd_off(D0, 0, 0)>(vb), h0 = tr_read<v_rd_off(D0, 0, 1)>(vb), l1 = tr_read<v_rd_off(D0, 1, 0)>(vb), h1 = tr_read<v_rd_off(D0, 1, 1)>(vb);
;   const s16x4 l2 = tr_read<v_rd_off(D0, 2, 0)>(vb), h2 = tr_read<v_rd_off(D0, 2, 1)>(vb), l3 = tr_read<v_rd_off(D0, 3, 0)>(vb), h3 = tr_read<v_rd_off(D0, 3, 1)>(vb);
;   asm volatile("s_waitcnt lgkmcnt(0)" ::: "memory"); SBAR();
;     ...
;   od = __builtin_amdgcn_mfma_f32_32x32x16_bf16(pa0, PK(l0, h0), od, 0, 0, 0);
;   od = __builtin_amdgcn_mfma_f32_32x32x16_bf16(pa1, PK(l1, h1), od, 0, 0, 0);
;   od = __builtin_amdgcn_mfma_f32_32x32x16_bf16(pa2, PK(l2, h2), od, 0, 0, 0);
;   od = __builtin_amdgcn_mfma_f32_32x32x16_bf16(pa3, PK(l3, h3), od, 0, 0, 0);
;     ...
; }
; __device__ __forceinline__ void pv_d0(f32x16* o, int vb, bf16x8 pa0, bf16x8 pa1, bf16x8 pa2, bf16x8 pa3) {
;   pv_one<0>(o[0], vb, pa0, pa1, pa2, pa3); pv_one<1>(o[1], vb, pa0, pa1, pa2, pa3); pv_one<2>(o[2], vb, pa0, pa1, pa2, pa3); pv_one<3>(o[3], vb, pa0, pa1, pa2, pa3);
; }
; __device__ __forceinline__ void pack_p(const f32x16& p0, const f32x16& p1, bf16x8& pa0, bf16x8& pa1, bf16x8& pa2, bf16x8& pa3) {
;     ...
;   PK4(p0, 0, pa0); PK4(p0, 8, pa1); PK4(p1, 0, pa2); PK4(p1, 8, pa3);
;     ...
; }
; template <int DQK>
; __device__ __forceinline__ void partialSM(f32x16& p0, f32x16& p1, float& m_reg, float& mn, float& alpha) {
;   constexpr float SCALE = DQK == 128 ? 0.088388347648318440f : 0.072168783648703220f;
;   constexpr float C = SCALE * LOG2E;
;   float pmax = p0[0];
; #pragma unroll
;   for (int r = 1; r < 16; ++r) pmax = fmaxf(pmax, p0[r]);
; #pragma unroll
;   for (int r = 0; r < 16; ++r) pmax = fmaxf(pmax, p1[r]);
;   { auto rr = __builtin_amdgcn_permlane32_swap(__float_as_uint(pmax), __float_as_uint(pmax), false, false);
;     pmax = fmaxf(__uint_as_float(rr[0]), __uint_as_float(rr[1])); }
;   if (__builtin_expect(__all(pmax - m_reg <= THR / SCALE), 1)) { mn = m_reg; alpha = 1.f; }
;   else { mn = fmaxf(m_reg, pmax); alpha = __builtin_amdgcn_exp2f((m_reg - mn) * C); m_reg = mn; }
;   const float mnC = -mn * C;
; #pragma unroll
;   for (int r = 0; r < 16; ++r) p0[r] = fmaf(p0[r], C, mnC);
; #pragma unroll
;   for (int r = 0; r < 16; ++r) p1[r] = fmaf(p1[r], C, mnC);
; #pragma unroll
.LBB0_900:
	v_cndmask_b32_e64 v205, v207, v205, s[6:7]
	s_barrier
	v_mul_f32_e32 v207, 0xbdd53b94, v205
	v_fmamk_f32 v82, v82, 0x3dd53b94, v207
	v_fmamk_f32 v83, v83, 0x3dd53b94, v207
	v_fmamk_f32 v84, v84, 0x3dd53b94, v207
	v_fmamk_f32 v85, v85, 0x3dd53b94, v207
	v_fmamk_f32 v86, v86, 0x3dd53b94, v207
	v_fmamk_f32 v87, v87, 0x3dd53b94, v207
	v_fmamk_f32 v88, v88, 0x3dd53b94, v207
	v_fmamk_f32 v89, v89, 0x3dd53b94, v207
	v_fmamk_f32 v90, v90, 0x3dd53b94, v207
	v_fmamk_f32 v91, v91, 0x3dd53b94, v207
	v_fmamk_f32 v92, v92, 0x3dd53b94, v207
	v_fmamk_f32 v93, v93, 0x3dd53b94, v207
	v_fmamk_f32 v94, v94, 0x3dd53b94, v207
	v_fmamk_f32 v95, v95, 0x3dd53b94, v207
	v_fmamk_f32 v96, v96, 0x3dd53b94, v207
	v_fmamk_f32 v97, v97, 0x3dd53b94, v207
	v_fmamk_f32 v66, v66, 0x3dd53b94, v207
	v_fmamk_f32 v67, v67, 0x3dd53b94, v207
	v_fmamk_f32 v68, v68, 0x3dd53b94, v207
	v_fmamk_f32 v69, v69, 0x3dd53b94, v207
	v_fmamk_f32 v70, v70, 0x3dd53b94, v207
	v_fmamk_f32 v71, v71, 0x3dd53b94, v207
	v_fmamk_f32 v72, v72, 0x3dd53b94, v207
	v_fmamk_f32 v73, v73, 0x3dd53b94, v207
	v_fmamk_f32 v74, v74, 0x3dd53b94, v207
	v_fmamk_f32 v75, v75, 0x3dd53b94, v207
	v_fmamk_f32 v76, v76, 0x3dd53b94, v207
	v_fmamk_f32 v77, v77, 0x3dd53b94, v207
	v_fmamk_f32 v78, v78, 0x3dd53b94, v207
	v_fmamk_f32 v79, v79, 0x3dd53b94, v207
	v_fmamk_f32 v80, v80, 0x3dd53b94, v207
	v_fmac_f32_e32 v207, 0x3dd53b94, v81
	v_exp_f32_e32 v81, v82
	v_exp_f32_e32 v82, v83
	v_exp_f32_e32 v83, v84
	v_exp_f32_e32 v84, v85
	v_exp_f32_e32 v85, v86
	v_exp_f32_e32 v86, v87
	v_exp_f32_e32 v87, v88
	v_exp_f32_e32 v88, v89
	v_exp_f32_e32 v89, v90
	v_exp_f32_e32 v90, v91
	v_exp_f32_e32 v91, v92
	v_exp_f32_e32 v92, v93
	v_exp_f32_e32 v93, v94
	v_exp_f32_e32 v94, v95
	v_exp_f32_e32 v95, v96
	v_exp_f32_e32 v96, v97
	v_exp_f32_e32 v97, v66
	v_add_f32_e32 v66, 0, v81
	v_add_f32_e32 v66, v82, v66
	v_add_f32_e32 v66, v83, v66
	v_add_f32_e32 v66, v84, v66
	v_add_f32_e32 v66, v85, v66
	v_add_f32_e32 v66, v86, v66
	v_add_f32_e32 v66, v87, v66
	v_add_f32_e32 v66, v88, v66
	v_add_f32_e32 v66, v89, v66
	v_add_f32_e32 v66, v90, v66
	v_add_f32_e32 v66, v91, v66
	v_add_f32_e32 v66, v92, v66
	v_add_f32_e32 v66, v93, v66
	v_exp_f32_e32 v208, v67
	v_add_f32_e32 v66, v94, v66
	v_exp_f32_e32 v209, v68
	v_add_f32_e32 v66, v95, v66
	v_exp_f32_e32 v210, v69
	v_add_f32_e32 v66, v96, v66
	v_exp_f32_e32 v211, v70
	v_add_f32_e32 v66, v97, v66
	v_exp_f32_e32 v212, v71
	v_add_f32_e32 v66, v208, v66
	v_exp_f32_e32 v213, v72
	v_add_f32_e32 v66, v209, v66
	v_exp_f32_e32 v214, v73
	v_add_f32_e32 v66, v210, v66
	v_exp_f32_e32 v215, v74
	v_add_f32_e32 v66, v211, v66
	v_exp_f32_e32 v216, v75
	v_add_f32_e32 v66, v212, v66
	v_exp_f32_e32 v217, v76
	v_add_f32_e32 v66, v213, v66
	v_exp_f32_e32 v218, v77
	v_add_f32_e32 v66, v214, v66
	v_exp_f32_e32 v219, v78
	v_add_f32_e32 v66, v215, v66
	v_exp_f32_e32 v220, v79
	v_add_f32_e32 v66, v216, v66
	v_exp_f32_e32 v221, v80
	v_add_f32_e32 v66, v217, v66
	v_exp_f32_e32 v207, v207
	v_add_f32_e32 v66, v218, v66
	v_add_f32_e32 v66, v219, v66
	v_add_f32_e32 v66, v220, v66
	v_add_f32_e32 v66, v221, v66
	v_add_f32_e32 v66, v207, v66
	v_mov_b32_e32 v67, v66
	s_nop 1
	v_permlane32_swap_b32_e32 v66, v67
	v_cvt_pk_bf16_f32 v68, v81, v82
	v_cvt_pk_bf16_f32 v69, v83, v84
	v_cvt_pk_bf16_f32 v70, v85, v86
	v_cvt_pk_bf16_f32 v71, v87, v88
	v_cvt_pk_bf16_f32 v72, v89, v90
	v_cvt_pk_bf16_f32 v73, v91, v92
	v_cvt_pk_bf16_f32 v74, v93, v94
	v_cvt_pk_bf16_f32 v75, v95, v96
	v_cvt_pk_bf16_f32 v76, v97, v208
	v_cvt_pk_bf16_f32 v77, v209, v210
	v_cvt_pk_bf16_f32 v78, v211, v212
	v_cvt_pk_bf16_f32 v79, v213, v214
	v_cvt_pk_bf16_f32 v80, v215, v216
	v_cvt_pk_bf16_f32 v81, v217, v218
	v_cvt_pk_bf16_f32 v82, v219, v220
	v_cvt_pk_bf16_f32 v83, v221, v207
	v_permlane32_swap_b32_e32 v68, v70
	v_permlane32_swap_b32_e32 v69, v71
	v_permlane32_swap_b32_e32 v72, v74
	v_permlane32_swap_b32_e32 v73, v75
	v_permlane32_swap_b32_e32 v76, v78
	v_permlane32_swap_b32_e32 v77, v79
	v_permlane32_swap_b32_e32 v80, v82
	v_permlane32_swap_b32_e32 v81, v83
	v_lshl_add_u32 v96, s38, 14, v204
	s_setprio 1
	ds_read_b64_tr_b16 v[84:85], v96 offset:0
	ds_read_b64_tr_b16 v[86:87], v96 offset:0x800
	ds_read_b64_tr_b16 v[88:89], v96 offset:0x1000
	ds_read_b64_tr_b16 v[90:91], v96 offset:0x1800
	ds_read_b64_tr_b16 v[92:93], v96 offset:0x2000
	ds_read_b64_tr_b16 v[94:95], v96 offset:0x2800
	ds_read_b64_tr_b16 v[208:209], v96 offset:0x3000
	ds_read_b64_tr_b16 v[210:211], v96 offset:0x3800
	s_waitcnt lgkmcnt(0)
	s_nop 0
	v_mfma_f32_32x32x16_bf16 v[2:17], v[68:71], v[84:87], v[2:17]
	ds_read_b64_tr_b16 v[84:85], v96 offset:0x200
	ds_read_b64_tr_b16 v[86:87], v96 offset:0xa00
	v_mfma_f32_32x32x16_bf16 v[2:17], v[72:75], v[88:91], v[2:17]
	ds_read_b64_tr_b16 v[88:89], v96 offset:0x1200
	ds_read_b64_tr_b16 v[90:91], v96 offset:0x1a00
	v_mfma_f32_32x32x16_bf16 v[2:17], v[76:79], v[92:95], v[2:17]
	ds_read_b64_tr_b16 v[92:93], v96 offset:0x2200
	ds_read_b64_tr_b16 v[94:95], v96 offset:0x2a00
	ds_read_b64_tr_b16 v[212:213], v96 offset:0x3200
	ds_read_b64_tr_b16 v[214:215], v96 offset:0x3a00
	s_waitcnt lgkmcnt(0)
	v_mfma_f32_32x32x16_bf16 v[2:17], v[80:83], v[208:211], v[2:17]
	v_mfma_f32_32x32x16_bf16 v[50:65], v[68:71], v[84:87], v[50:65]
	ds_read_b64_tr_b16 v[84:85], v96 offset:0x400
	ds_read_b64_tr_b16 v[86:87], v96 offset:0xc00
	v_mfma_f32_32x32x16_bf16 v[50:65], v[72:75], v[88:91], v[50:65]
	ds_read_b64_tr_b16 v[88:89], v96 offset:0x1400
	ds_read_b64_tr_b16 v[90:91], v96 offset:0x1c00
	v_mfma_f32_32x32x16_bf16 v[50:65], v[76:79], v[92:95], v[50:65]
	ds_read_b64_tr_b16 v[92:93], v96 offset:0x2400
	ds_read_b64_tr_b16 v[94:95], v96 offset:0x2c00
	ds_read_b64_tr_b16 v[208:209], v96 offset:0x3400
	ds_read_b64_tr_b16 v[210:211], v96 offset:0x3c00
	s_waitcnt lgkmcnt(0)
	v_mfma_f32_32x32x16_bf16 v[50:65], v[80:83], v[212:215], v[50:65]
	v_mfma_f32_32x32x16_bf16 v[34:49], v[68:71], v[84:87], v[34:49]
	ds_read_b64_tr_b16 v[84:85], v96 offset:0x600
	ds_read_b64_tr_b16 v[86:87], v96 offset:0xe00
	v_mfma_f32_32x32x16_bf16 v[34:49], v[72:75], v[88:91], v[34:49]
	ds_read_b64_tr_b16 v[88:89], v96 offset:0x1600
	ds_read_b64_tr_b16 v[90:91], v96 offset:0x1e00
	v_mfma_f32_32x32x16_bf16 v[34:49], v[76:79], v[92:95], v[34:49]
	ds_read_b64_tr_b16 v[92:93], v96 offset:0x2600
	ds_read_b64_tr_b16 v[94:95], v96 offset:0x2e00
	ds_read_b64_tr_b16 v[212:213], v96 offset:0x3600
	ds_read_b64_tr_b16 v[214:215], v96 offset:0x3e00
	s_waitcnt lgkmcnt(0)
	v_mfma_f32_32x32x16_bf16 v[34:49], v[80:83], v[208:211], v[34:49]
	v_mfma_f32_32x32x16_bf16 v[18:33], v[68:71], v[84:87], v[18:33]
	s_andn2_b64 vcc, exec, s[18:19]
	v_mfma_f32_32x32x16_bf16 v[18:33], v[72:75], v[88:91], v[18:33]
	v_mfma_f32_32x32x16_bf16 v[18:33], v[76:79], v[92:95], v[18:33]
	v_mfma_f32_32x32x16_bf16 v[18:33], v[80:83], v[212:215], v[18:33]
	s_setprio 0
	s_cbranch_vccnz .LBB0_902
; #define SWRITE(b, i) do { *(bf16x8*)(V_lds + (b) * SH::V + vst0) = sr_[i].vs0; *(bf16x8*)(V_lds + (b) * SH::V + vst1) = sr_[i].vs1; \
;     _Pragma("unroll") for (int q_ = 0; q_ < KPT; ++q_) *(bf16x8*)(K_lds + (b) * SH::K + KSWZ(krow[q_], kcol[q_] * 2)) = sr_[i].ks[q_]; } while (0)
; template <int DQK, int MODE, int SDEPTH, int ldq, int ldk, int ldv, int ldo, int ldg> ...
;     ...
;       if (j + 1 < NT) { asm volatile("s_waitcnt vmcnt(0)" ::: "memory"); SWRITE(bsel ^ 1, 0); }
	s_xor_b32 s6, s38, 1
	s_lshl_b32 s7, s6, 14
	s_add_i32 s7, s7, 0
	v_add_u32_e32 v68, s7, v183
	s_lshl_b32 s6, s6, 13
	s_waitcnt vmcnt(0)
	ds_write_b128 v68, v[98:101]
	v_add_u32_e32 v68, s7, v182
	s_add_i32 s7, s7, s6
	ds_write_b128 v68, v[102:105]
	v_add3_u32 v68, s7, v184, v185
	ds_write_b128 v68, v[106:109] offset:32768
	v_add3_u32 v68, s7, v186, v187
	ds_write_b128 v68, v[110:113] offset:32768
	v_add3_u32 v68, s7, v188, v189
	ds_write_b128 v68, v[142:145] offset:32768

; #define SLOAD(i, k0) do { sr_[i].vs0 = *reinterpret_cast<const bf16x8*>(&Vh[(long)((k0) + sr) * ldv + sc]); sr_[i].vs1 = *reinterpret_cast<const bf16x8*>(&Vh[(long)((k0) + 32 + sr) * ldv + sc]); \
;     _Pragma("unroll") for (int q_ = 0; q_ < KPT; ++q_) sr_[i].ks[q_] = *reinterpret_cast<const bf16x8*>(&Kh[(long)((k0) + krow[q_]) * ldk + kcol[q_]]); } while (0)
; template <int DQK, int MODE, int SDEPTH, int ldq, int ldk, int ldv, int ldo, int ldg> ...
;     ...
;       if (j + 1 < NT) SLOAD(0, (j + 1) * KVBLK);
.Lm2_B_entry:
	v_lshl_add_u64 v[224:225], s[26:27], 0, v[178:179]
	v_add_co_u32_e32 v226, vcc, 0x1c010000, v224
	s_nop 1
	v_addc_co_u32_e32 v227, vcc, 0, v225, vcc
	v_add_co_u32_e32 v224, vcc, 0x1c018000, v224
	s_nop 1
	v_addc_co_u32_e32 v225, vcc, 0, v225, vcc
	global_load_dwordx4 v[98:101], v[226:227], off
	global_load_dwordx4 v[102:105], v[224:225], off
	v_lshl_add_u64 v[224:225], s[26:27], 0, v[176:177]
	v_lshl_add_u64 v[226:227], s[26:27], 0, v[174:175]
	global_load_dwordx4 v[106:109], v[224:225], off
	global_load_dwordx4 v[110:113], v[226:227], off
	v_lshl_add_u64 v[224:225], s[26:27], 0, v[172:173]
	global_load_dwordx4 v[142:145], v[224:225], off
	v_lshl_add_u64 v[172:173], v[172:173], 0, s[12:13]
	v_lshl_add_u64 v[174:175], v[174:175], 0, s[12:13]
	v_lshl_add_u64 v[176:177], v[176:177], 0, s[12:13]
	v_lshl_add_u64 v[178:179], v[178:179], 0, s[16:17]
	s_barrier
	s_branch .Lm2_BX
.Lm2_BY:
	s_cmp_gt_u32 s3, 34
	s_cbranch_scc1 .Lm2_BY_nl
	v_lshl_add_u64 v[224:225], s[26:27], 0, v[178:179]
	v_add_co_u32_e32 v226, vcc, 0x1c010000, v224
	s_nop 1
	v_addc_co_u32_e32 v227, vcc, 0, v225, vcc
	v_add_co_u32_e32 v224, vcc, 0x1c018000, v224
	s_nop 1
	v_addc_co_u32_e32 v225, vcc, 0, v225, vcc
	global_load_dwordx4 v[98:101], v[226:227], off
	global_load_dwordx4 v[102:105], v[224:225], off
	v_lshl_add_u64 v[224:225], s[26:27], 0, v[176:177]
	v_lshl_add_u64 v[226:227], s[26:27], 0, v[174:175]
	global_load_dwordx4 v[106:109], v[224:225], off
	global_load_dwordx4 v[110:113], v[226:227], off
	v_lshl_add_u64 v[224:225], s[26:27], 0, v[172:173]
	global_load_dwordx4 v[142:145], v[224:225], off
	v_lshl_add_u64 v[172:173], v[172:173], 0, s[12:13]
	v_lshl_add_u64 v[174:175], v[174:175], 0, s[12:13]
	v_lshl_add_u64 v[176:177], v[176:177], 0, s[12:13]
	v_lshl_add_u64 v[178:179], v[178:179], 0, s[16:17]
; template <int D0> __device__ __forceinline__ void pv_one(f32x16& od, int vb, bf16x8 pa0, bf16x8 pa1, bf16x8 pa2, bf16x8 pa3) {
;   const s16x4 l0 = tr_read<v_rd_off(D0, 0, 0)>(vb), h0 = tr_read<v_rd_off(D0, 0, 1)>(vb), l1 = tr_read<v_rd_off(D0, 1, 0)>(vb), h1 = tr_read<v_rd_off(D0, 1, 1)>(vb);
;   const s16x4 l2 = tr_read<v_rd_off(D0, 2, 0)>(vb), h2 = tr_read<v_rd_off(D0, 2, 1)>(vb), l3 = tr_read<v_rd_off(D0, 3, 0)>(vb), h3 = tr_read<v_rd_off(D0, 3, 1)>(vb);
;   asm volatile("s_waitcnt lgkmcnt(0)" ::: "memory"); SBAR();
;     ...
;   od = __builtin_amdgcn_mfma_f32_32x32x16_bf16(pa0, PK(l0, h0), od, 0, 0, 0);
;   od = __builtin_amdgcn_mfma_f32_32x32x16_bf16(pa1, PK(l1, h1), od, 0, 0, 0);
;   od = __builtin_amdgcn_mfma_f32_32x32x16_bf16(pa2, PK(l2, h2), od, 0, 0, 0);
;   od = __builtin_amdgcn_mfma_f32_32x32x16_bf16(pa3, PK(l3, h3), od, 0, 0, 0);
;     ...
; }
; __device__ __forceinline__ void pv_d0(f32x16* o, int vb, bf16x8 pa0, bf16x8 pa1, bf16x8 pa2, bf16x8 pa3) {
;   pv_one<0>(o[0], vb, pa0, pa1, pa2, pa3); pv_one<1>(o[1], vb, pa0, pa1, pa2, pa3); pv_one<2>(o[2], vb, pa0, pa1, pa2, pa3); pv_one<3>(o[3], vb, pa0, pa1, pa2, pa3);
; }
; __device__ __forceinline__ void pack_p(const f32x16& p0, const f32x16& p1, bf16x8& pa0, bf16x8& pa1, bf16x8& pa2, bf16x8& pa3) {
;     ...
;   PK4(p0, 0, pa0); PK4(p0, 8, pa1); PK4(p1, 0, pa2); PK4(p1, 8, pa3);
;     ...
; }
; template <int DQK>
; __device__ __forceinline__ void partialSM(f32x16& p0, f32x16& p1, float& m_reg, float& mn, float& alpha) {
;   constexpr float SCALE = DQK == 128 ? 0.088388347648318440f : 0.072168783648703220f;
;   constexpr float C = SCALE * LOG2E;
;   float pmax = p0[0];
; #pragma unroll
;   for (int r = 1; r < 16; ++r) pmax = fmaxf(pmax, p0[r]);
; #pragma unroll
;   for (int r = 0; r < 16; ++r) pmax = fmaxf(pmax, p1[r]);
;   { auto rr = __builtin_amdgcn_permlane32_swap(__float_as_uint(pmax), __float_as_uint(pmax), false, false);
;     pmax = fmaxf(__uint_as_float(rr[0]), __uint_as_float(rr[1])); }
;   if (__builtin_expect(__all(pmax - m_reg <= THR / SCALE), 1)) { mn = m_reg; alpha = 1.f; }
;   else { mn = fmaxf(m_reg, pmax); alpha = __builtin_amdgcn_exp2f((m_reg - mn) * C); m_reg = mn; }
;   const float mnC = -mn * C;
; #pragma unroll
;   for (int r = 0; r < 16; ++r) p0[r] = fmaf(p0[r], C, mnC);
; #pragma unroll
;   for (int r = 0; r < 16; ++r) p1[r] = fmaf(p1[r], C, mnC);
; #pragma unroll
.Lm2_BY_nl:
	v_mul_f32_e32 v207, 0xbdd53b94, v205
	v_fmamk_f32 v82, v82, 0x3dd53b94, v207
	v_fmamk_f32 v83, v83, 0x3dd53b94, v207
	v_fmamk_f32 v84, v84, 0x3dd53b94, v207
	v_fmamk_f32 v85, v85, 0x3dd53b94, v207
	v_fmamk_f32 v86, v86, 0x3dd53b94, v207
	v_fmamk_f32 v87, v87, 0x3dd53b94, v207
	v_fmamk_f32 v88, v88, 0x3dd53b94, v207
	v_fmamk_f32 v89, v89, 0x3dd53b94, v207
	v_fmamk_f32 v90, v90, 0x3dd53b94, v207
	v_fmamk_f32 v91, v91, 0x3dd53b94, v207
	v_fmamk_f32 v92, v92, 0x3dd53b94, v207
	v_fmamk_f32 v93, v93, 0x3dd53b94, v207
	v_fmamk_f32 v94, v94, 0x3dd53b94, v207
	v_fmamk_f32 v95, v95, 0x3dd53b94, v207
	v_fmamk_f32 v96, v96, 0x3dd53b94, v207
	v_fmamk_f32 v97, v97, 0x3dd53b94, v207
	v_fmamk_f32 v66, v66, 0x3dd53b94, v207
	v_fmamk_f32 v67, v67, 0x3dd53b94, v207
	v_fmamk_f32 v68, v68, 0x3dd53b94, v207
	v_fmamk_f32 v69, v69, 0x3dd53b94, v207
	v_fmamk_f32 v70, v70, 0x3dd53b94, v207
	v_fmamk_f32 v71, v71, 0x3dd53b94, v207
	v_fmamk_f32 v72, v72, 0x3dd53b94, v207
	v_fmamk_f32 v73, v73, 0x3dd53b94, v207
	v_fmamk_f32 v74, v74, 0x3dd53b94, v207
	v_fmamk_f32 v75, v75, 0x3dd53b94, v207
	v_fmamk_f32 v76, v76, 0x3dd53b94, v207
	v_fmamk_f32 v77, v77, 0x3dd53b94, v207
	v_fmamk_f32 v78, v78, 0x3dd53b94, v207
	v_fmamk_f32 v79, v79, 0x3dd53b94, v207
	v_fmamk_f32 v80, v80, 0x3dd53b94, v207
	v_fmac_f32_e32 v207, 0x3dd53b94, v81
	v_exp_f32_e32 v81, v82
	v_exp_f32_e32 v82, v83
	v_exp_f32_e32 v83, v84
	v_exp_f32_e32 v84, v85
	v_exp_f32_e32 v85, v86
	v_exp_f32_e32 v86, v87
	v_exp_f32_e32 v87, v88
	v_exp_f32_e32 v88, v89
	v_exp_f32_e32 v89, v90
	v_exp_f32_e32 v90, v91
	v_exp_f32_e32 v91, v92
	v_exp_f32_e32 v92, v93
	v_exp_f32_e32 v93, v94
	v_exp_f32_e32 v94, v95
	v_exp_f32_e32 v95, v96
	v_exp_f32_e32 v96, v97
	v_exp_f32_e32 v97, v66
	v_add_f32_e32 v66, 0, v81
	v_add_f32_e32 v66, v82, v66
	v_add_f32_e32 v66, v83, v66
	v_add_f32_e32 v66, v84, v66
	v_add_f32_e32 v66, v85, v66
	v_add_f32_e32 v66, v86, v66
	v_add_f32_e32 v66, v87, v66
	v_add_f32_e32 v66, v88, v66
	v_add_f32_e32 v66, v89, v66
	v_add_f32_e32 v66, v90, v66
	v_add_f32_e32 v66, v91, v66
	v_add_f32_e32 v66, v92, v66
	v_add_f32_e32 v66, v93, v66
	v_exp_f32_e32 v208, v67
	v_add_f32_e32 v66, v94, v66
	v_exp_f32_e32 v209, v68
	v_add_f32_e32 v66, v95, v66
	v_exp_f32_e32 v210, v69
	v_add_f32_e32 v66, v96, v66
	v_exp_f32_e32 v211, v70
	v_add_f32_e32 v66, v97, v66
	v_exp_f32_e32 v212, v71
	v_add_f32_e32 v66, v208, v66
	v_exp_f32_e32 v213, v72
	v_add_f32_e32 v66, v209, v66
	v_exp_f32_e32 v214, v73
	v_add_f32_e32 v66, v210, v66
	v_exp_f32_e32 v215, v74
	v_add_f32_e32 v66, v211, v66
	v_exp_f32_e32 v216, v75
	v_add_f32_e32 v66, v212, v66
	v_exp_f32_e32 v217, v76
	v_add_f32_e32 v66, v213, v66
	v_exp_f32_e32 v218, v77
	v_add_f32_e32 v66, v214, v66
	v_exp_f32_e32 v219, v78
	v_add_f32_e32 v66, v215, v66
	v_exp_f32_e32 v220, v79
	v_add_f32_e32 v66, v216, v66
	v_exp_f32_e32 v221, v80
	v_add_f32_e32 v66, v217, v66
	v_exp_f32_e32 v207, v207
	v_add_f32_e32 v66, v218, v66
	v_add_f32_e32 v66, v219, v66
	v_add_f32_e32 v66, v220, v66
	v_add_f32_e32 v66, v221, v66
	v_add_f32_e32 v66, v207, v66
	v_mov_b32_e32 v67, v66
	s_nop 1
	v_permlane32_swap_b32_e32 v66, v67
	v_cvt_pk_bf16_f32 v68, v81, v82
	v_cvt_pk_bf16_f32 v69, v83, v84
	v_cvt_pk_bf16_f32 v70, v85, v86
	v_cvt_pk_bf16_f32 v71, v87, v88
	v_cvt_pk_bf16_f32 v72, v89, v90
	v_cvt_pk_bf16_f32 v73, v91, v92
	v_cvt_pk_bf16_f32 v74, v93, v94
	v_cvt_pk_bf16_f32 v75, v95, v96
	v_cvt_pk_bf16_f32 v76, v97, v208
	v_cvt_pk_bf16_f32 v77, v209, v210
	v_cvt_pk_bf16_f32 v78, v211, v212
	v_cvt_pk_bf16_f32 v79, v213, v214
	v_cvt_pk_bf16_f32 v80, v215, v216
	v_cvt_pk_bf16_f32 v81, v217, v218
	v_cvt_pk_bf16_f32 v82, v219, v220
	v_cvt_pk_bf16_f32 v83, v221, v207
	v_permlane32_swap_b32_e32 v68, v70
	v_permlane32_swap_b32_e32 v69, v71
	v_permlane32_swap_b32_e32 v72, v74
	v_permlane32_swap_b32_e32 v73, v75
	v_permlane32_swap_b32_e32 v76, v78
	v_permlane32_swap_b32_e32 v77, v79
	v_permlane32_swap_b32_e32 v80, v82
	v_permlane32_swap_b32_e32 v81, v83
	v_lshl_add_u32 v96, s38, 14, v204
	s_setprio 1
	ds_read_b64_tr_b16 v[84:85], v96 offset:0
	ds_read_b64_tr_b16 v[86:87], v96 offset:0x800
	ds_read_b64_tr_b16 v[88:89], v96 offset:0x1000
	ds_read_b64_tr_b16 v[90:91], v96 offset:0x1800
	ds_read_b64_tr_b16 v[92:93], v96 offset:0x2000
	ds_read_b64_tr_b16 v[94:95], v96 offset:0x2800
	ds_read_b64_tr_b16 v[208:209], v96 offset:0x3000
	ds_read_b64_tr_b16 v[210:211], v96 offset:0x3800
	s_waitcnt lgkmcnt(0)
	s_nop 0
	v_mfma_f32_32x32x16_bf16 v[2:17], v[68:71], v[84:87], v[2:17]
	ds_read_b64_tr_b16 v[84:85], v96 offset:0x200
	ds_read_b64_tr_b16 v[86:87], v96 offset:0xa00
	v_mfma_f32_32x32x16_bf16 v[2:17], v[72:75], v[88:91], v[2:17]
	ds_read_b64_tr_b16 v[88:89], v96 offset:0x1200
	ds_read_b64_tr_b16 v[90:91], v96 offset:0x1a00
	v_mfma_f32_32x32x16_bf16 v[2:17], v[76:79], v[92:95], v[2:17]
	ds_read_b64_tr_b16 v[92:93], v96 offset:0x2200
	ds_read_b64_tr_b16 v[94:95], v96 offset:0x2a00
	ds_read_b64_tr_b16 v[212:213], v96 offset:0x3200
	ds_read_b64_tr_b16 v[214:215], v96 offset:0x3a00
	s_waitcnt lgkmcnt(0)
	v_mfma_f32_32x32x16_bf16 v[2:17], v[80:83], v[208:211], v[2:17]
	v_mfma_f32_32x32x16_bf16 v[50:65], v[68:71], v[84:87], v[50:65]
	ds_read_b64_tr_b16 v[84:85], v96 offset:0x400
	ds_read_b64_tr_b16 v[86:87], v96 offset:0xc00
	v_mfma_f32_32x32x16_bf16 v[50:65], v[72:75], v[88:91], v[50:65]
	ds_read_b64_tr_b16 v[88:89], v96 offset:0x1400
	ds_read_b64_tr_b16 v[90:91], v96 offset:0x1c00
	v_mfma_f32_32x32x16_bf16 v[50:65], v[76:79], v[92:95], v[50:65]
	ds_read_b64_tr_b16 v[92:93], v96 offset:0x2400
	ds_read_b64_tr_b16 v[94:95], v96 offset:0x2c00
	ds_read_b64_tr_b16 v[208:209], v96 offset:0x3400
	ds_read_b64_tr_b16 v[210:211], v96 offset:0x3c00
	s_waitcnt lgkmcnt(0)
	v_mfma_f32_32x32x16_bf16 v[50:65], v[80:83], v[212:215], v[50:65]
	v_mfma_f32_32x32x16_bf16 v[34:49], v[68:71], v[84:87], v[34:49]
	ds_read_b64_tr_b16 v[84:85], v96 offset:0x600
	ds_read_b64_tr_b16 v[86:87], v96 offset:0xe00
	v_mfma_f32_32x32x16_bf16 v[34:49], v[72:75], v[88:91], v[34:49]
	ds_read_b64_tr_b16 v[88:89], v96 offset:0x1600
	ds_read_b64_tr_b16 v[90:91], v96 offset:0x1e00
	v_mfma_f32_32x32x16_bf16 v[34:49], v[76:79], v[92:95], v[34:49]
	ds_read_b64_tr_b16 v[92:93], v96 offset:0x2600
	ds_read_b64_tr_b16 v[94:95], v96 offset:0x2e00
	ds_read_b64_tr_b16 v[212:213], v96 offset:0x3600
	ds_read_b64_tr_b16 v[214:215], v96 offset:0x3e00
	s_waitcnt lgkmcnt(0)
	v_mfma_f32_32x32x16_bf16 v[34:49], v[80:83], v[208:211], v[34:49]
	v_mfma_f32_32x32x16_bf16 v[18:33], v[68:71], v[84:87], v[18:33]
	v_mfma_f32_32x32x16_bf16 v[18:33], v[72:75], v[88:91], v[18:33]
	v_mfma_f32_32x32x16_bf16 v[18:33], v[76:79], v[92:95], v[18:33]
	v_mfma_f32_32x32x16_bf16 v[18:33], v[80:83], v[212:215], v[18:33]
	s_setprio 0
	v_add_f32_e32 v66, v66, v67
	v_fmac_f32_e32 v66, v169, v206
	s_waitcnt lgkmcnt(0)
	v_mov_b32_e32 v169, v66
	s_barrier
	s_cmp_eq_u32 s3, 36
	s_cbranch_scc1 .LBB0_904

; #define SBAR() __builtin_amdgcn_sched_barrier(0)
; #define SLOAD(i, k0) do { sr_[i].vs0 = *reinterpret_cast<const bf16x8*>(&Vh[(long)((k0) + sr) * ldv + sc]); sr_[i].vs1 = *reinterpret_cast<const bf16x8*>(&Vh[(long)((k0) + 32 + sr) * ldv + sc]); \
;     _Pragma("unroll") for (int q_ = 0; q_ < KPT; ++q_) sr_[i].ks[q_] = *reinterpret_cast<const bf16x8*>(&Kh[(long)((k0) + krow[q_]) * ldk + kcol[q_]]); } while (0)
; #define SWRITE(b, i) do { *(bf16x8*)(V_lds + (b) * SH::V + vst0) = sr_[i].vs0; *(bf16x8*)(V_lds + (b) * SH::V + vst1) = sr_[i].vs1; \
;     _Pragma("unroll") for (int q_ = 0; q_ < KPT; ++q_) *(bf16x8*)(K_lds + (b) * SH::K + KSWZ(krow[q_], kcol[q_] * 2)) = sr_[i].ks[q_]; } while (0)
; #define RESC(a) do { if (__any((a) < 1.f)) { if (hi == 0) al_l[r32] = (a); asm volatile("s_waitcnt lgkmcnt(0)" ::: "memory"); \
;     _Pragma("unroll") for (int d = 0; d < 4; ++d) _Pragma("unroll") for (int r = 0; r < 16; ++r) o[d][r] *= al_l[crow(r, hi)]; } } while (0)
; #define PART(P0, P1, tj, MN, AL) do { if constexpr (MODE == 0) partialSM<DQK>(P0, P1, m_reg, MN, AL); else ret_weights(P0, P1, TKIND(tj), nlane - (float)(64 * (tj) - 256), lf2, lb2); } while (0)
; #define FIN(P0, P1, AL) do { if constexpr (MODE == 0) finishSM(P0, P1, AL, l_reg, pa0, pa1, pa2, pa3); else pack_p(P0, P1, pa0, pa1, pa2, pa3); } while (0)
; template <int DQK>
; __device__ __forceinline__ void partialSM(f32x16& p0, f32x16& p1, float& m_reg, float& mn, float& alpha) {
;     ...
;   if (__builtin_expect(__all(pmax - m_reg <= THR / SCALE), 1)) { mn = m_reg; alpha = 1.f; }
;   else { mn = fmaxf(m_reg, pmax); alpha = __builtin_amdgcn_exp2f((m_reg - mn) * C); m_reg = mn; }
; template <int DQK, int MODE, int SDEPTH, int ldq, int ldk, int ldv, int ldo, int ldg> ...
;     ...
;     for (int j = 0; j < NT; ++j) {
;       const int bsel = j & 1;
;       if (j + 1 < NT) SLOAD(0, (j + 1) * KVBLK);
;       SBAR(); QKT(pA0, pA1, K_lds + bsel * SH::K);
;       PART(pA0, pA1, j, mnA, alA);
;       if constexpr (MODE == 0) RESC(alA);
;       FIN(pA0, pA1, alA); SBAR();
;       pv_d0(o, vb0 + bsel * SH::V, pa0, pa1, pa2, pa3);
;       if (j + 1 < NT) { asm volatile("s_waitcnt vmcnt(0)" ::: "memory"); SWRITE(bsel ^ 1, 0); }
;       __syncthreads();
.Lm2_B_900:
	v_cndmask_b32_e64 v205, v207, v205, s[6:7]
	s_cmp_gt_u32 s3, 34
	s_cbranch_scc1 .Lm2_BX_nw
	s_xor_b32 s44, s38, 1
	s_lshl_b32 s45, s44, 14
	s_add_i32 s45, s45, 0
	v_add_u32_e32 v224, s45, v183
	s_lshl_b32 s44, s44, 13
	s_waitcnt vmcnt(0)
	ds_write_b128 v224, v[98:101]
	v_add_u32_e32 v224, s45, v182
	s_add_i32 s45, s45, s44
	ds_write_b128 v224, v[102:105]
	v_add3_u32 v224, s45, v184, v185
	ds_write_b128 v224, v[106:109] offset:32768
	v_add3_u32 v224, s45, v186, v187
	ds_write_b128 v224, v[110:113] offset:32768
	v_add3_u32 v224, s45, v188, v189
	ds_write_b128 v224, v[142:145] offset:32768
.Lm2_BX_nw:
	s_waitcnt lgkmcnt(0)
	s_barrier
	s_add_i32 s3, s3, 1
	s_branch .Lm2_BY

; template <int DQK>
; __device__ __forceinline__ void partialSM(f32x16& p0, f32x16& p1, float& m_reg, float& mn, float& alpha) {
;     ...
;   float pmax = p0[0];
; #pragma unroll
;   for (int r = 1; r < 16; ++r) pmax = fmaxf(pmax, p0[r]);
; #pragma unroll
;   for (int r = 0; r < 16; ++r) pmax = fmaxf(pmax, p1[r]);
;   { auto rr = __builtin_amdgcn_permlane32_swap(__float_as_uint(pmax), __float_as_uint(pmax), false, false);
;     pmax = fmaxf(__uint_as_float(rr[0]), __uint_as_float(rr[1])); }
;   if (__builtin_expect(__all(pmax - m_reg <= THR / SCALE), 1)) { mn = m_reg; alpha = 1.f; }
;   else { mn = fmaxf(m_reg, pmax); alpha = __builtin_amdgcn_exp2f((m_reg - mn) * C); m_reg = mn; }
.LBB0_909:
	s_and_b32 s30, s29, 1
	s_mul_i32 s6, s30, 0x6000
	v_add_u32_e32 v214, s6, v191
	v_add_u32_e32 v70, v214, v192
	ds_read_b128 v[66:69], v70 offset:32768
	ds_read_b128 v[70:73], v70 offset:45056
	v_add_u32_e32 v210, v214, v193
	ds_read_b128 v[206:209], v210 offset:32768
	ds_read_b128 v[210:213], v210 offset:45056
	v_add_u32_e32 v215, v214, v201
	s_waitcnt lgkmcnt(3)
	v_mfma_f32_32x32x16_bf16 v[82:97], v[66:69], v[114:117], 0
	s_waitcnt lgkmcnt(2)
	v_mfma_f32_32x32x16_bf16 v[66:81], v[70:73], v[114:117], 0
	s_waitcnt lgkmcnt(1)
	v_mfma_f32_32x32x16_bf16 v[82:97], v[206:209], v[118:121], v[82:97]
	s_waitcnt lgkmcnt(0)
	v_mfma_f32_32x32x16_bf16 v[66:81], v[210:213], v[118:121], v[66:81]
	v_add_u32_e32 v210, v214, v194
	ds_read_b128 v[206:209], v210 offset:32768
	ds_read_b128 v[210:213], v210 offset:45056
	s_waitcnt lgkmcnt(1)
	v_mfma_f32_32x32x16_bf16 v[82:97], v[206:209], v[122:125], v[82:97]
	s_waitcnt lgkmcnt(0)
	v_mfma_f32_32x32x16_bf16 v[66:81], v[210:213], v[122:125], v[66:81]
	v_add_u32_e32 v210, v214, v195
	ds_read_b128 v[206:209], v210 offset:32768
	ds_read_b128 v[210:213], v210 offset:45056
	s_waitcnt lgkmcnt(1)
	v_mfma_f32_32x32x16_bf16 v[82:97], v[206:209], v[126:129], v[82:97]
	s_waitcnt lgkmcnt(0)
	v_mfma_f32_32x32x16_bf16 v[66:81], v[210:213], v[126:129], v[66:81]
	v_add_u32_e32 v210, v214, v196
	ds_read_b128 v[206:209], v210 offset:32768
	ds_read_b128 v[210:213], v210 offset:45056
	s_waitcnt lgkmcnt(1)
	v_mfma_f32_32x32x16_bf16 v[82:97], v[206:209], v[130:133], v[82:97]
	s_waitcnt lgkmcnt(0)
	v_mfma_f32_32x32x16_bf16 v[66:81], v[210:213], v[130:133], v[66:81]
	v_add_u32_e32 v210, v214, v197
	ds_read_b128 v[206:209], v210 offset:32768
	ds_read_b128 v[210:213], v210 offset:45056
	s_waitcnt lgkmcnt(1)
	v_mfma_f32_32x32x16_bf16 v[82:97], v[206:209], v[134:137], v[82:97]
	s_waitcnt lgkmcnt(0)
	v_mfma_f32_32x32x16_bf16 v[66:81], v[210:213], v[134:137], v[66:81]
	v_add_u32_e32 v210, v214, v198
	ds_read_b128 v[206:209], v210 offset:32768
	ds_read_b128 v[210:213], v210 offset:45056
	s_waitcnt lgkmcnt(1)
	v_mfma_f32_32x32x16_bf16 v[82:97], v[206:209], v[138:141], v[82:97]
	s_waitcnt lgkmcnt(0)
	v_mfma_f32_32x32x16_bf16 v[66:81], v[210:213], v[138:141], v[66:81]
	v_add_u32_e32 v210, v214, v199
	ds_read_b128 v[206:209], v210 offset:32768
	ds_read_b128 v[210:213], v210 offset:45056
	s_waitcnt lgkmcnt(1)
	v_mfma_f32_32x32x16_bf16 v[82:97], v[206:209], v[142:145], v[82:97]
	s_waitcnt lgkmcnt(0)
	v_mfma_f32_32x32x16_bf16 v[66:81], v[210:213], v[142:145], v[66:81]
	v_add_u32_e32 v210, v214, v200
	ds_read_b128 v[206:209], v210 offset:32768
	ds_read_b128 v[210:213], v210 offset:45056
	s_waitcnt lgkmcnt(1)
	v_mfma_f32_32x32x16_bf16 v[82:97], v[206:209], v[150:153], v[82:97]
	s_waitcnt lgkmcnt(0)
	v_mfma_f32_32x32x16_bf16 v[66:81], v[210:213], v[150:153], v[66:81]
	ds_read_b128 v[206:209], v215 offset:32768
	ds_read_b128 v[210:213], v215 offset:45056
	v_add_u32_e32 v215, v214, v202
	v_add_u32_e32 v214, v214, v203
	s_waitcnt lgkmcnt(1)
	v_mfma_f32_32x32x16_bf16 v[82:97], v[206:209], v[154:157], v[82:97]
	s_waitcnt lgkmcnt(0)
	v_mfma_f32_32x32x16_bf16 v[66:81], v[210:213], v[154:157], v[66:81]
	ds_read_b128 v[206:209], v215 offset:32768
	ds_read_b128 v[210:213], v215 offset:45056
	s_waitcnt lgkmcnt(1)
	v_mfma_f32_32x32x16_bf16 v[82:97], v[206:209], v[158:161], v[82:97]
	ds_read_b128 v[206:209], v214 offset:32768
	ds_read_b128 v[214:217], v214 offset:45056
	s_waitcnt lgkmcnt(1)
	v_mfma_f32_32x32x16_bf16 v[82:97], v[206:209], v[162:165], v[82:97]
	v_mfma_f32_32x32x16_bf16 v[66:81], v[210:213], v[158:161], v[66:81]
	s_nop 10
	v_max_f32_e32 v206, v83, v83
	v_max_f32_e32 v207, v82, v82
	v_max_f32_e32 v206, v207, v206
	v_max3_f32 v206, v206, v84, v85
	v_max3_f32 v206, v206, v86, v87
	v_max3_f32 v206, v206, v88, v89
	v_max3_f32 v206, v206, v90, v91
	s_waitcnt lgkmcnt(0)
	v_mfma_f32_32x32x16_bf16 v[66:81], v[214:217], v[162:165], v[66:81]
	v_max3_f32 v206, v206, v92, v93
	v_max3_f32 v206, v206, v94, v95
	v_max3_f32 v206, v206, v96, v97
	s_nop 8
	v_max3_f32 v206, v206, v66, v67
	v_max3_f32 v206, v206, v68, v69
	v_max3_f32 v206, v206, v70, v71
	v_max3_f32 v206, v206, v72, v73
	v_max3_f32 v206, v206, v74, v75
	v_max3_f32 v206, v206, v76, v77
	v_max3_f32 v206, v206, v78, v79
	v_max3_f32 v206, v206, v80, v81
	v_mov_b32_e32 v207, v206
	s_nop 1
	v_permlane32_swap_b32_e32 v206, v207
	v_max_f32_e32 v207, v207, v207
	v_max_f32_e32 v206, v206, v206
	v_max_f32_e32 v206, v206, v207
	v_max_f32_e32 v207, v205, v205
	v_max_f32_e32 v207, v207, v206
	v_sub_f32_e32 v208, v206, v205
	v_sub_f32_e32 v206, v205, v207
	v_mul_f32_e32 v206, 0x3dd53b94, v206
	v_exp_f32_e32 v206, v206
	v_cmp_ge_f32_e32 vcc, s28, v208
	s_cmp_eq_u64 vcc, exec
	s_cselect_b64 s[6:7], -1, 0
	v_cndmask_b32_e64 v206, v206, 1.0, s[6:7]
	v_cmp_gt_f32_e32 vcc, 1.0, v206
	s_cbranch_vccz .LBB0_913
	s_and_saveexec_b64 s[54:55], s[4:5]
	ds_write_b32 v190, v206 offset:128
	s_or_b64 exec, exec, s[54:55]
	s_waitcnt lgkmcnt(0)
	v_add_u32_e32 v220, v171, v168
	ds_read_b128 v[208:211], v220 offset:224
	ds_read_b128 v[212:215], v220 offset:192
	ds_read_b128 v[216:219], v220 offset:160
	ds_read_b128 v[220:223], v220 offset:128
	s_waitcnt lgkmcnt(3)
	v_pk_mul_f32 v[14:15], v[14:15], v[208:209]
	s_waitcnt lgkmcnt(2)
	v_pk_mul_f32 v[10:11], v[10:11], v[212:213]
	s_waitcnt lgkmcnt(1)
	v_pk_mul_f32 v[6:7], v[6:7], v[216:217]
	v_pk_mul_f32 v[16:17], v[16:17], v[210:211]
	v_pk_mul_f32 v[12:13], v[12:13], v[214:215]
	v_pk_mul_f32 v[8:9], v[8:9], v[218:219]
	s_waitcnt lgkmcnt(0)
	v_pk_mul_f32 v[4:5], v[4:5], v[222:223]
	v_pk_mul_f32 v[2:3], v[2:3], v[220:221]
	v_pk_mul_f32 v[62:63], v[62:63], v[208:209]
	v_pk_mul_f32 v[58:59], v[58:59], v[212:213]
	v_pk_mul_f32 v[54:55], v[54:55], v[216:217]
	v_pk_mul_f32 v[64:65], v[64:65], v[210:211]
	v_pk_mul_f32 v[60:61], v[60:61], v[214:215]
	v_pk_mul_f32 v[56:57], v[56:57], v[218:219]
	v_pk_mul_f32 v[52:53], v[52:53], v[222:223]
	v_pk_mul_f32 v[50:51], v[50:51], v[220:221]
	v_pk_mul_f32 v[46:47], v[46:47], v[208:209]
	v_pk_mul_f32 v[42:43], v[42:43], v[212:213]
	v_pk_mul_f32 v[38:39], v[38:39], v[216:217]
	v_pk_mul_f32 v[48:49], v[48:49], v[210:211]
	v_pk_mul_f32 v[44:45], v[44:45], v[214:215]
	v_pk_mul_f32 v[40:41], v[40:41], v[218:219]
	v_pk_mul_f32 v[36:37], v[36:37], v[222:223]
	v_pk_mul_f32 v[34:35], v[34:35], v[220:221]
	v_pk_mul_f32 v[30:31], v[30:31], v[208:209]
	v_pk_mul_f32 v[26:27], v[26:27], v[212:213]
	v_pk_mul_f32 v[22:23], v[22:23], v[216:217]
	v_pk_mul_f32 v[32:33], v[32:33], v[210:211]
	v_pk_mul_f32 v[28:29], v[28:29], v[214:215]
	v_pk_mul_f32 v[24:25], v[24:25], v[218:219]
	v_pk_mul_f32 v[20:21], v[20:21], v[222:223]
	v_pk_mul_f32 v[18:19], v[18:19], v[220:221]
